# adds FFN conv-gate epilogue: the 4 weight vectors needed first are loaded before the chunk's store and waited with vmcnt(5); the other 4 waited right before first use
# baseline (speedup 1.0000x reference)
; DI float sigmoidf_(float x) { return 1.f / (1.f + __expf(-x)); }
; DI void up_epilogue(const PRef& p, int l, const f32x4 (&acc)[2][2][4][2], int brow, int bcol, int wr, int wc, int fr, int fq, float* exch) {
;     ...
; #pragma unroll
;         for (int j = 0; j < 4; ++j) {
;           const float a = acc[ai][0][m][n][j], g = acc[ai][1][m][n][j];
;           float pr1 = dppz<0x111>(a), pr2 = dppz<0x112>(a);
;           if (m == 0) {
;             if (fr == 0) { pr1 = p63a[j]; pr2 = p62a[j]; }
;             if (fr == 1) { pr2 = p63a[j]; }
;           } else {
;             const float am = acc[ai][0][m > 0 ? m - 1 : 0][n][j];
;             const float mir = dppz<0x140>(am);
;             const float swp = dppz<0xB1>(mir);
;             if (fr == 0) { pr1 = mir; }
;             if (fr < 2) { pr2 = swp; }
;           }
;           const float cv = bsa[j] + w0a[j] * pr2 + w1a[j] * pr1 + w2a[j] * a;
;           o[n * 4 + j] = cv * sigmoidf_(cv) * g;
.LBB0_1044:
	s_or_b64 exec, exec, s[2:3]
	s_waitcnt lgkmcnt(1)
	v_cndmask_b32_e64 v171, v220, v171, s[16:17]
	v_cndmask_b32_e64 v170, v219, v170, s[16:17]
	s_waitcnt lgkmcnt(0)
	v_cndmask_b32_e64 v170, v170, v174, s[18:19]
	v_cndmask_b32_e64 v171, v171, v175, s[18:19]
	v_cndmask_b32_e64 v174, v217, v174, s[16:17]
	v_cndmask_b32_e64 v175, v218, v175, s[16:17]
	s_waitcnt vmcnt(4)
	v_pk_fma_f32 v[158:159], v[158:159], v[170:171], v[166:167]
	v_lshl_add_u64 v[190:191], v[190:191], 1, s[90:91]
	v_pk_fma_f32 v[158:159], v[162:163], v[174:175], v[158:159]
	v_mov_b32_e32 v171, 0
	v_pk_fma_f32 v[154:155], v[126:127], v[154:155], v[158:159]
	v_mov_b32_e32 v174, 0
	v_mul_f32_e32 v158, 0xbfb8aa3b, v154
	v_mul_f32_e32 v159, 0xbfb8aa3b, v155
	v_exp_f32_e32 v158, v158
	v_exp_f32_e32 v159, v159
	v_mov_b32_e32 v175, 0
	v_pk_add_f32 v[158:159], v[158:159], 1.0 op_sel_hi:[1,0]
	s_nop 0
	v_div_scale_f32 v162, s[2:3], v159, v159, 1.0
	v_rcp_f32_e32 v163, v162
	s_nop 0
	v_fma_f32 v166, -v162, v163, 1.0
	v_fmac_f32_e32 v163, v166, v163
	v_div_scale_f32 v166, vcc, 1.0, v159, 1.0
	v_mul_f32_e32 v167, v166, v163
	v_fma_f32 v170, -v162, v167, v166
	v_fmac_f32_e32 v167, v170, v163
	v_fma_f32 v162, -v162, v167, v166
	v_div_fmas_f32 v162, v162, v163, v167
	v_div_fixup_f32 v159, v162, v159, 1.0
	v_div_scale_f32 v162, s[2:3], v158, v158, 1.0
	v_rcp_f32_e32 v163, v162
	s_nop 0
	v_fma_f32 v166, -v162, v163, 1.0
	v_fmac_f32_e32 v163, v166, v163
	v_div_scale_f32 v166, vcc, 1.0, v158, 1.0
	v_mul_f32_e32 v167, v166, v163
	v_fma_f32 v170, -v162, v167, v166
	v_fmac_f32_e32 v167, v170, v163
	v_fma_f32 v162, -v162, v167, v166
	v_div_fmas_f32 v162, v162, v163, v167
	v_div_fixup_f32 v158, v162, v158, 1.0
	v_pk_mul_f32 v[154:155], v[154:155], v[158:159]
	v_cndmask_b32_e64 v159, v216, v173, s[16:17]
	v_cndmask_b32_e64 v158, v215, v172, s[16:17]
	v_cndmask_b32_e64 v158, v158, v176, s[18:19]
	v_cndmask_b32_e64 v159, v159, v177, s[18:19]
	v_cndmask_b32_e64 v162, v16, v176, s[16:17]
	v_cndmask_b32_e64 v163, v214, v177, s[16:17]
	v_pk_fma_f32 v[158:159], v[160:161], v[158:159], v[168:169]
	v_pk_mul_f32 v[154:155], v[118:119], v[154:155]
	v_pk_fma_f32 v[158:159], v[164:165], v[162:163], v[158:159]
	v_mov_b32_dpp v166, v126 row_mirror row_mask:0xf bank_mask:0xf bound_ctrl:1
	v_pk_fma_f32 v[156:157], v[128:129], v[156:157], v[158:159]
	v_mov_b32_dpp v168, v127 row_mirror row_mask:0xf bank_mask:0xf bound_ctrl:1
	v_mul_f32_e32 v16, 0xbfb8aa3b, v156
	v_exp_f32_e32 v158, v16
	v_mul_f32_e32 v16, 0xbfb8aa3b, v157
	v_exp_f32_e32 v159, v16
	v_mov_b32_dpp v165, v166 quad_perm:[1,0,3,2] row_mask:0xf bank_mask:0xf bound_ctrl:1
	v_mov_b32_dpp v169, v168 quad_perm:[1,0,3,2] row_mask:0xf bank_mask:0xf bound_ctrl:1
	v_mov_b32_dpp v164, v110 row_shr:1 row_mask:0xf bank_mask:0xf bound_ctrl:1
	v_pk_add_f32 v[158:159], v[158:159], 1.0 op_sel_hi:[1,0]
	v_mov_b32_dpp v167, v111 row_shr:1 row_mask:0xf bank_mask:0xf bound_ctrl:1
	v_div_scale_f32 v16, s[2:3], v159, v159, 1.0
	v_rcp_f32_e32 v160, v16
	v_cndmask_b32_e64 v164, v164, v166, s[16:17]
	v_mov_b32_dpp v166, v110 row_mirror row_mask:0xf bank_mask:0xf bound_ctrl:1
	v_mov_b32_e32 v172, 0
	v_fma_f32 v161, -v16, v160, 1.0
	v_fmac_f32_e32 v160, v161, v160
	v_div_scale_f32 v161, vcc, 1.0, v159, 1.0
	v_mul_f32_e32 v162, v161, v160
	v_fma_f32 v163, -v16, v162, v161
	v_fmac_f32_e32 v162, v163, v160
	v_fma_f32 v16, -v16, v162, v161
	v_div_fmas_f32 v16, v16, v160, v162
	v_div_fixup_f32 v159, v16, v159, 1.0
	v_div_scale_f32 v16, s[2:3], v158, v158, 1.0
	v_rcp_f32_e32 v160, v16
	v_mov_b32_e32 v173, 0
	v_mov_b32_e32 v170, 0
	v_mov_b32_e32 v176, 0
	v_fma_f32 v161, -v16, v160, 1.0
	v_fmac_f32_e32 v160, v161, v160
	v_div_scale_f32 v161, vcc, 1.0, v158, 1.0
	v_mul_f32_e32 v162, v161, v160
	v_fma_f32 v163, -v16, v162, v161
	v_fmac_f32_e32 v162, v163, v160
	v_fma_f32 v16, -v16, v162, v161
	v_div_fmas_f32 v16, v16, v160, v162
	v_div_fixup_f32 v158, v16, v158, 1.0
	v_pk_mul_f32 v[156:157], v[156:157], v[158:159]
	v_mov_b32_dpp v159, v122 row_shr:2 row_mask:0xf bank_mask:0xf bound_ctrl:1
	v_mov_b32_dpp v161, v123 row_shr:2 row_mask:0xf bank_mask:0xf bound_ctrl:1
	v_cndmask_b32_e64 v130, v159, v130, s[16:17]
	v_cndmask_b32_e64 v131, v161, v131, s[16:17]
	v_mov_b32_dpp v158, v122 row_shr:1 row_mask:0xf bank_mask:0xf bound_ctrl:1
	v_mov_b32_dpp v160, v123 row_shr:1 row_mask:0xf bank_mask:0xf bound_ctrl:1
	v_cndmask_b32_e64 v131, v131, v151, s[18:19]
	v_cndmask_b32_e64 v130, v130, v150, s[18:19]
	v_cndmask_b32_e64 v151, v160, v151, s[16:17]
	v_cndmask_b32_e64 v150, v158, v150, s[16:17]
	s_waitcnt vmcnt(0)
; DI unsigned pack2(float a, float b) { f32v2 v = {a, b}; return __builtin_bit_cast(unsigned, __builtin_convertvector(v, bf16v2)); }
; DI float sigmoidf_(float x) { return 1.f / (1.f + __expf(-x)); }
; DI void up_epilogue(const PRef& p, int l, const f32x4 (&acc)[2][2][4][2], int brow, int bcol, int wr, int wc, int fr, int fq, float* exch) {
;     ...
;       for (int n = 0; n < 2; ++n) {
;         const int c = cw0 + n * 4;
;         const float4 w0 = *reinterpret_cast<const float4*>(cwp + c), w1 = *reinterpret_cast<const float4*>(cwp + DFF + c);
;         const float4 w2 = *reinterpret_cast<const float4*>(cwp + 2 * DFF + c), bs = *reinterpret_cast<const float4*>(cbp + c);
;         const float w0a[4] = {w0.x, w0.y, w0.z, w0.w}, w1a[4] = {w1.x, w1.y, w1.z, w1.w}, w2a[4] = {w2.x, w2.y, w2.z, w2.w}, bsa[4] = {bs.x, bs.y, bs.z, bs.w};
;         float p62a[4] = {0.f, 0.f, 0.f, 0.f}, p63a[4] = {0.f, 0.f, 0.f, 0.f};
;         if (m == 0 && sp > 0) {
;           const float4 p62 = *reinterpret_cast<const float4*>(exch + (((sp - 1) * 2 + 0) * 128 + tc0 + n * 4));
;           const float4 p63 = *reinterpret_cast<const float4*>(exch + (((sp - 1) * 2 + 1) * 128 + tc0 + n * 4));
;           p62a[0] = p62.x; p62a[1] = p62.y; p62a[2] = p62.z; p62a[3] = p62.w;
;           p63a[0] = p63.x; p63a[1] = p63.y; p63a[2] = p63.z; p63a[3] = p63.w;
;         }
; #pragma unroll
;         for (int j = 0; j < 4; ++j) {
;           const float a = acc[ai][0][m][n][j], g = acc[ai][1][m][n][j];
;           float pr1 = dppz<0x111>(a), pr2 = dppz<0x112>(a);
;           if (m == 0) {
;             if (fr == 0) { pr1 = p63a[j]; pr2 = p62a[j]; }
;             if (fr == 1) { pr2 = p63a[j]; }
;           } else {
;             const float am = acc[ai][0][m > 0 ? m - 1 : 0][n][j];
;             const float mir = dppz<0x140>(am);
;             const float swp = dppz<0xB1>(mir);
;             if (fr == 0) { pr1 = mir; }
;             if (fr < 2) { pr2 = swp; }
;           }
;           const float cv = bsa[j] + w0a[j] * pr2 + w1a[j] * pr1 + w2a[j] * a;
;           o[n * 4 + j] = cv * sigmoidf_(cv) * g;
;         }
;       }
;       uint4 ov; ov.x = pack2(o[0], o[1]); ov.y = pack2(o[2], o[3]); ov.z = pack2(o[4], o[5]); ov.w = pack2(o[6], o[7]);
;       *reinterpret_cast<uint4*>(hmid + (size_t)(brow + ai * HALF + wr * 64 + m * 16 + fr) * DFF + cw0) = ov;
	v_pk_fma_f32 v[130:131], v[138:139], v[130:131], v[146:147]
	v_pk_mul_f32 v[156:157], v[120:121], v[156:157]
	v_pk_fma_f32 v[130:131], v[142:143], v[150:151], v[130:131]
	v_add_u32_e32 v16, s62, v205
	v_pk_fma_f32 v[130:131], v[122:123], v[134:135], v[130:131]
	v_mov_b32_dpp v162, v110 row_shr:2 row_mask:0xf bank_mask:0xf bound_ctrl:1
	v_mul_f32_e32 v134, 0xbfb8aa3b, v130
	v_mul_f32_e32 v135, 0xbfb8aa3b, v131
	v_exp_f32_e32 v134, v134
	v_exp_f32_e32 v135, v135
	v_mov_b32_dpp v163, v111 row_shr:2 row_mask:0xf bank_mask:0xf bound_ctrl:1
	v_cndmask_b32_e64 v163, v163, v169, s[14:15]
	v_cndmask_b32_e64 v162, v162, v165, s[14:15]
	v_pk_add_f32 v[134:135], v[134:135], 1.0 op_sel_hi:[1,0]
	v_cndmask_b32_e64 v165, v167, v168, s[16:17]
	v_div_scale_f32 v138, s[2:3], v135, v135, 1.0
	v_rcp_f32_e32 v139, v138
	v_mov_b32_dpp v168, v111 row_mirror row_mask:0xf bank_mask:0xf bound_ctrl:1
	v_mov_b32_dpp v167, v95 row_shr:1 row_mask:0xf bank_mask:0xf bound_ctrl:1
	v_mov_b32_e32 v177, 0
	v_fma_f32 v142, -v138, v139, 1.0
	v_fmac_f32_e32 v139, v142, v139
	v_div_scale_f32 v142, vcc, 1.0, v135, 1.0
	v_mul_f32_e32 v143, v142, v139
	v_fma_f32 v146, -v138, v143, v142
	v_fmac_f32_e32 v143, v146, v139
	v_fma_f32 v138, -v138, v143, v142
	v_div_fmas_f32 v138, v138, v139, v143
	v_div_fixup_f32 v135, v138, v135, 1.0
	v_div_scale_f32 v138, s[2:3], v134, v134, 1.0
	v_rcp_f32_e32 v139, v138
	v_mov_b32_dpp v169, v168 quad_perm:[1,0,3,2] row_mask:0xf bank_mask:0xf bound_ctrl:1
	v_fma_f32 v142, -v138, v139, 1.0
	v_fmac_f32_e32 v139, v142, v139
	v_div_scale_f32 v142, vcc, 1.0, v134, 1.0
	v_mul_f32_e32 v143, v142, v139
	v_fma_f32 v146, -v138, v143, v142
	v_fmac_f32_e32 v143, v146, v139
	v_fma_f32 v138, -v138, v143, v142
	v_div_fmas_f32 v138, v138, v139, v143
	v_div_fixup_f32 v134, v138, v134, 1.0
	v_pk_mul_f32 v[130:131], v[130:131], v[134:135]
	v_mov_b32_dpp v138, v124 row_shr:1 row_mask:0xf bank_mask:0xf bound_ctrl:1
	v_pk_mul_f32 v[134:135], v[114:115], v[130:131]
	v_mov_b32_dpp v130, v124 row_shr:2 row_mask:0xf bank_mask:0xf bound_ctrl:1
	v_mov_b32_dpp v131, v125 row_shr:2 row_mask:0xf bank_mask:0xf bound_ctrl:1
	v_cndmask_b32_e64 v130, v130, v132, s[16:17]
	v_cndmask_b32_e64 v131, v131, v133, s[16:17]
	v_mov_b32_dpp v139, v125 row_shr:1 row_mask:0xf bank_mask:0xf bound_ctrl:1
	v_cndmask_b32_e64 v131, v131, v153, s[18:19]
	v_cndmask_b32_e64 v130, v130, v152, s[18:19]
	v_cndmask_b32_e64 v133, v139, v153, s[16:17]
	v_cndmask_b32_e64 v132, v138, v152, s[16:17]
	v_pk_fma_f32 v[130:131], v[140:141], v[130:131], v[148:149]
	s_nop 0
	v_pk_fma_f32 v[130:131], v[144:145], v[132:133], v[130:131]
	s_nop 0
	v_pk_fma_f32 v[130:131], v[124:125], v[136:137], v[130:131]
	s_nop 0
	v_mul_f32_e32 v132, 0xbfb8aa3b, v130
	v_mul_f32_e32 v133, 0xbfb8aa3b, v131
	v_exp_f32_e32 v132, v132
	v_exp_f32_e32 v133, v133
	s_nop 0
	v_pk_add_f32 v[132:133], v[132:133], 1.0 op_sel_hi:[1,0]
	s_nop 0
	v_div_scale_f32 v136, s[2:3], v133, v133, 1.0
	v_rcp_f32_e32 v137, v136
	s_nop 0
	v_fma_f32 v138, -v136, v137, 1.0
	v_fmac_f32_e32 v137, v138, v137
	v_div_scale_f32 v138, vcc, 1.0, v133, 1.0
	v_mul_f32_e32 v139, v138, v137
	v_fma_f32 v140, -v136, v139, v138
	v_fmac_f32_e32 v139, v140, v137
	v_fma_f32 v136, -v136, v139, v138
	v_div_fmas_f32 v136, v136, v137, v139
	v_div_fixup_f32 v133, v136, v133, 1.0
	v_div_scale_f32 v136, s[2:3], v132, v132, 1.0
	v_rcp_f32_e32 v137, v136
	s_nop 0
	v_fma_f32 v138, -v136, v137, 1.0
	v_fmac_f32_e32 v137, v138, v137
	v_div_scale_f32 v138, vcc, 1.0, v132, 1.0
	v_mul_f32_e32 v139, v138, v137
	v_fma_f32 v140, -v136, v139, v138
	v_fmac_f32_e32 v139, v140, v137
	v_fma_f32 v136, -v136, v139, v138
	v_div_fmas_f32 v136, v136, v137, v139
	v_div_fixup_f32 v132, v136, v132, 1.0
	v_pk_mul_f32 v[130:131], v[130:131], v[132:133]
	v_cvt_pk_bf16_f32 v132, v134, v135
	v_pk_mul_f32 v[136:137], v[116:117], v[130:131]
	v_cvt_pk_bf16_f32 v130, v154, v155
	v_cvt_pk_bf16_f32 v131, v156, v157
	v_cvt_pk_bf16_f32 v133, v136, v137
	v_mad_i64_i32 v[134:135], s[2:3], v16, s40, v[190:191]
	global_load_dwordx4 v[146:149], v[198:199], off
	s_nop 0
	global_load_dwordx4 v[150:153], v[196:197], off
	s_nop 0
	global_load_dwordx4 v[154:157], v[194:195], off
	s_nop 0
	global_load_dwordx4 v[158:161], v[192:193], off
	s_nop 0
	global_store_dwordx4 v[134:135], v[130:133], off
	s_nop 3
	global_load_dwordx4 v[130:133], v[198:199], off offset:16
	s_nop 0
	global_load_dwordx4 v[138:141], v[196:197], off offset:16
	s_nop 0
	global_load_dwordx4 v[134:137], v[194:195], off offset:16
	s_nop 0
	global_load_dwordx4 v[142:145], v[192:193], off offset:16
	s_nop 0
	s_waitcnt vmcnt(5)
; DI float sigmoidf_(float x) { return 1.f / (1.f + __expf(-x)); }
; DI void up_epilogue(const PRef& p, int l, const f32x4 (&acc)[2][2][4][2], int brow, int bcol, int wr, int wc, int fr, int fq, float* exch) {
;     ...
;       for (int n = 0; n < 2; ++n) {
;         const int c = cw0 + n * 4;
;         const float4 w0 = *reinterpret_cast<const float4*>(cwp + c), w1 = *reinterpret_cast<const float4*>(cwp + DFF + c);
;         const float4 w2 = *reinterpret_cast<const float4*>(cwp + 2 * DFF + c), bs = *reinterpret_cast<const float4*>(cbp + c);
;         const float w0a[4] = {w0.x, w0.y, w0.z, w0.w}, w1a[4] = {w1.x, w1.y, w1.z, w1.w}, w2a[4] = {w2.x, w2.y, w2.z, w2.w}, bsa[4] = {bs.x, bs.y, bs.z, bs.w};
;         float p62a[4] = {0.f, 0.f, 0.f, 0.f}, p63a[4] = {0.f, 0.f, 0.f, 0.f};
;         if (m == 0 && sp > 0) {
;           const float4 p62 = *reinterpret_cast<const float4*>(exch + (((sp - 1) * 2 + 0) * 128 + tc0 + n * 4));
;           const float4 p63 = *reinterpret_cast<const float4*>(exch + (((sp - 1) * 2 + 1) * 128 + tc0 + n * 4));
;           p62a[0] = p62.x; p62a[1] = p62.y; p62a[2] = p62.z; p62a[3] = p62.w;
;           p63a[0] = p63.x; p63a[1] = p63.y; p63a[2] = p63.z; p63a[3] = p63.w;
;         }
; #pragma unroll
;         for (int j = 0; j < 4; ++j) {
;           const float a = acc[ai][0][m][n][j], g = acc[ai][1][m][n][j];
;           float pr1 = dppz<0x111>(a), pr2 = dppz<0x112>(a);
;           if (m == 0) {
;             if (fr == 0) { pr1 = p63a[j]; pr2 = p62a[j]; }
;             if (fr == 1) { pr2 = p63a[j]; }
;           } else {
;             const float am = acc[ai][0][m > 0 ? m - 1 : 0][n][j];
;             const float mir = dppz<0x140>(am);
;             const float swp = dppz<0xB1>(mir);
;             if (fr == 0) { pr1 = mir; }
;             if (fr < 2) { pr2 = swp; }
;           }
;           const float cv = bsa[j] + w0a[j] * pr2 + w1a[j] * pr1 + w2a[j] * a;
;           o[n * 4 + j] = cv * sigmoidf_(cv) * g;
	v_pk_fma_f32 v[146:147], v[146:147], v[162:163], v[158:159]
	s_nop 0
	v_pk_fma_f32 v[146:147], v[150:151], v[164:165], v[146:147]
	v_mov_b32_dpp v165, v166 quad_perm:[1,0,3,2] row_mask:0xf bank_mask:0xf bound_ctrl:1
	v_pk_fma_f32 v[146:147], v[110:111], v[154:155], v[146:147]
	v_mov_b32_dpp v164, v94 row_shr:1 row_mask:0xf bank_mask:0xf bound_ctrl:1
	v_mul_f32_e32 v150, 0xbfb8aa3b, v146
	v_mul_f32_e32 v151, 0xbfb8aa3b, v147
	v_exp_f32_e32 v150, v150
	v_exp_f32_e32 v151, v151
	v_cndmask_b32_e64 v164, v164, v166, s[16:17]
	v_mov_b32_dpp v166, v94 row_mirror row_mask:0xf bank_mask:0xf bound_ctrl:1
	v_pk_add_f32 v[150:151], v[150:151], 1.0 op_sel_hi:[1,0]
	s_nop 0
	v_div_scale_f32 v154, s[2:3], v151, v151, 1.0
	v_rcp_f32_e32 v155, v154
	s_nop 0
	v_fma_f32 v158, -v154, v155, 1.0
	v_fmac_f32_e32 v155, v158, v155
	v_div_scale_f32 v158, vcc, 1.0, v151, 1.0
	v_mul_f32_e32 v159, v158, v155
	v_fma_f32 v162, -v154, v159, v158
	v_fmac_f32_e32 v159, v162, v155
	v_fma_f32 v154, -v154, v159, v158
	v_div_fmas_f32 v154, v154, v155, v159
	v_div_fixup_f32 v151, v154, v151, 1.0
	v_div_scale_f32 v154, s[2:3], v150, v150, 1.0
	v_rcp_f32_e32 v155, v154
	s_nop 0
	v_fma_f32 v158, -v154, v155, 1.0
	v_fmac_f32_e32 v155, v158, v155
	v_div_scale_f32 v158, vcc, 1.0, v150, 1.0
	v_mul_f32_e32 v159, v158, v155
	v_fma_f32 v162, -v154, v159, v158
	v_fmac_f32_e32 v159, v162, v155
	v_fma_f32 v154, -v154, v159, v158
	v_div_fmas_f32 v154, v154, v155, v159
	v_div_fixup_f32 v150, v154, v150, 1.0
	v_mov_b32_dpp v158, v128 row_mirror row_mask:0xf bank_mask:0xf bound_ctrl:1
	v_mov_b32_dpp v162, v129 row_mirror row_mask:0xf bank_mask:0xf bound_ctrl:1
	v_pk_mul_f32 v[146:147], v[146:147], v[150:151]
	v_mov_b32_dpp v150, v112 row_shr:2 row_mask:0xf bank_mask:0xf bound_ctrl:1
	v_mov_b32_dpp v155, v158 quad_perm:[1,0,3,2] row_mask:0xf bank_mask:0xf bound_ctrl:1
	v_mov_b32_dpp v151, v113 row_shr:2 row_mask:0xf bank_mask:0xf bound_ctrl:1
	v_mov_b32_dpp v163, v162 quad_perm:[1,0,3,2] row_mask:0xf bank_mask:0xf bound_ctrl:1
	v_mov_b32_dpp v154, v112 row_shr:1 row_mask:0xf bank_mask:0xf bound_ctrl:1
	v_mov_b32_dpp v159, v113 row_shr:1 row_mask:0xf bank_mask:0xf bound_ctrl:1
	v_cndmask_b32_e64 v151, v151, v163, s[14:15]
	v_cndmask_b32_e64 v150, v150, v155, s[14:15]
	v_cndmask_b32_e64 v155, v159, v162, s[16:17]
	v_cndmask_b32_e64 v154, v154, v158, s[16:17]
	v_pk_fma_f32 v[148:149], v[148:149], v[150:151], v[160:161]
	v_pk_mul_f32 v[146:147], v[102:103], v[146:147]
	v_pk_fma_f32 v[148:149], v[152:153], v[154:155], v[148:149]
	v_mov_b32_dpp v162, v94 row_shr:2 row_mask:0xf bank_mask:0xf bound_ctrl:1
	v_pk_fma_f32 v[148:149], v[112:113], v[156:157], v[148:149]
	v_mov_b32_dpp v163, v95 row_shr:2 row_mask:0xf bank_mask:0xf bound_ctrl:1
	v_mul_f32_e32 v150, 0xbfb8aa3b, v148
	v_mul_f32_e32 v151, 0xbfb8aa3b, v149
	v_exp_f32_e32 v150, v150
	v_exp_f32_e32 v151, v151
	v_cndmask_b32_e64 v163, v163, v169, s[14:15]
	v_cndmask_b32_e64 v162, v162, v165, s[14:15]
	v_cndmask_b32_e64 v165, v167, v168, s[16:17]
	v_pk_add_f32 v[150:151], v[150:151], 1.0 op_sel_hi:[1,0]
	v_mov_b32_dpp v168, v95 row_mirror row_mask:0xf bank_mask:0xf bound_ctrl:1
	v_div_scale_f32 v152, s[2:3], v151, v151, 1.0
	v_rcp_f32_e32 v153, v152
	v_mov_b32_dpp v169, v168 quad_perm:[1,0,3,2] row_mask:0xf bank_mask:0xf bound_ctrl:1
	v_mov_b32_dpp v167, v79 row_shr:1 row_mask:0xf bank_mask:0xf bound_ctrl:1
	v_fma_f32 v154, -v152, v153, 1.0
	v_fmac_f32_e32 v153, v154, v153
	v_div_scale_f32 v154, vcc, 1.0, v151, 1.0
	v_mul_f32_e32 v155, v154, v153
	v_fma_f32 v156, -v152, v155, v154
	v_fmac_f32_e32 v155, v156, v153
	v_fma_f32 v152, -v152, v155, v154
	v_div_fmas_f32 v152, v152, v153, v155
	v_div_fixup_f32 v151, v152, v151, 1.0
	v_div_scale_f32 v152, s[2:3], v150, v150, 1.0
	v_rcp_f32_e32 v153, v152
	s_nop 0
	v_fma_f32 v154, -v152, v153, 1.0
	v_fmac_f32_e32 v153, v154, v153
	v_div_scale_f32 v154, vcc, 1.0, v150, 1.0
	v_mul_f32_e32 v155, v154, v153
	v_fma_f32 v156, -v152, v155, v154
	v_fmac_f32_e32 v155, v156, v153
	v_fma_f32 v152, -v152, v155, v154
	v_div_fmas_f32 v152, v152, v153, v155
	v_div_fixup_f32 v150, v152, v150, 1.0
	v_mov_b32_dpp v154, v122 row_mirror row_mask:0xf bank_mask:0xf bound_ctrl:1
	v_mov_b32_dpp v156, v123 row_mirror row_mask:0xf bank_mask:0xf bound_ctrl:1
	v_pk_mul_f32 v[148:149], v[148:149], v[150:151]
	v_mov_b32_dpp v150, v106 row_shr:2 row_mask:0xf bank_mask:0xf bound_ctrl:1
	v_mov_b32_dpp v153, v154 quad_perm:[1,0,3,2] row_mask:0xf bank_mask:0xf bound_ctrl:1
	v_mov_b32_dpp v151, v107 row_shr:2 row_mask:0xf bank_mask:0xf bound_ctrl:1
	v_mov_b32_dpp v157, v156 quad_perm:[1,0,3,2] row_mask:0xf bank_mask:0xf bound_ctrl:1
	v_mov_b32_dpp v152, v106 row_shr:1 row_mask:0xf bank_mask:0xf bound_ctrl:1
	v_mov_b32_dpp v155, v107 row_shr:1 row_mask:0xf bank_mask:0xf bound_ctrl:1
	v_cndmask_b32_e64 v151, v151, v157, s[14:15]
	v_cndmask_b32_e64 v150, v150, v153, s[14:15]
	v_cndmask_b32_e64 v153, v155, v156, s[16:17]
	v_cndmask_b32_e64 v152, v152, v154, s[16:17]
	s_waitcnt vmcnt(0)
; DI unsigned pack2(float a, float b) { f32v2 v = {a, b}; return __builtin_bit_cast(unsigned, __builtin_convertvector(v, bf16v2)); }
; DI float sigmoidf_(float x) { return 1.f / (1.f + __expf(-x)); }
; DI void up_epilogue(const PRef& p, int l, const f32x4 (&acc)[2][2][4][2], int brow, int bcol, int wr, int wc, int fr, int fq, float* exch) {
;     ...
;       for (int n = 0; n < 2; ++n) {
;         const int c = cw0 + n * 4;
;         const float4 w0 = *reinterpret_cast<const float4*>(cwp + c), w1 = *reinterpret_cast<const float4*>(cwp + DFF + c);
;         const float4 w2 = *reinterpret_cast<const float4*>(cwp + 2 * DFF + c), bs = *reinterpret_cast<const float4*>(cbp + c);
;         const float w0a[4] = {w0.x, w0.y, w0.z, w0.w}, w1a[4] = {w1.x, w1.y, w1.z, w1.w}, w2a[4] = {w2.x, w2.y, w2.z, w2.w}, bsa[4] = {bs.x, bs.y, bs.z, bs.w};
;         float p62a[4] = {0.f, 0.f, 0.f, 0.f}, p63a[4] = {0.f, 0.f, 0.f, 0.f};
;         if (m == 0 && sp > 0) {
;           const float4 p62 = *reinterpret_cast<const float4*>(exch + (((sp - 1) * 2 + 0) * 128 + tc0 + n * 4));
;           const float4 p63 = *reinterpret_cast<const float4*>(exch + (((sp - 1) * 2 + 1) * 128 + tc0 + n * 4));
;           p62a[0] = p62.x; p62a[1] = p62.y; p62a[2] = p62.z; p62a[3] = p62.w;
;           p63a[0] = p63.x; p63a[1] = p63.y; p63a[2] = p63.z; p63a[3] = p63.w;
;         }
; #pragma unroll
;         for (int j = 0; j < 4; ++j) {
;           const float a = acc[ai][0][m][n][j], g = acc[ai][1][m][n][j];
;           float pr1 = dppz<0x111>(a), pr2 = dppz<0x112>(a);
;           if (m == 0) {
;             if (fr == 0) { pr1 = p63a[j]; pr2 = p62a[j]; }
;             if (fr == 1) { pr2 = p63a[j]; }
;           } else {
;             const float am = acc[ai][0][m > 0 ? m - 1 : 0][n][j];
;             const float mir = dppz<0x140>(am);
;             const float swp = dppz<0xB1>(mir);
;             if (fr == 0) { pr1 = mir; }
;             if (fr < 2) { pr2 = swp; }
;           }
;           const float cv = bsa[j] + w0a[j] * pr2 + w1a[j] * pr1 + w2a[j] * a;
;           o[n * 4 + j] = cv * sigmoidf_(cv) * g;
;         }
;       }
;       uint4 ov; ov.x = pack2(o[0], o[1]); ov.y = pack2(o[2], o[3]); ov.z = pack2(o[4], o[5]); ov.w = pack2(o[6], o[7]);
;       *reinterpret_cast<uint4*>(hmid + (size_t)(brow + ai * HALF + wr * 64 + m * 16 + fr) * DFF + cw0) = ov;
	v_pk_fma_f32 v[130:131], v[130:131], v[150:151], v[142:143]
	v_pk_mul_f32 v[148:149], v[104:105], v[148:149]
	v_pk_fma_f32 v[130:131], v[138:139], v[152:153], v[130:131]
	s_nop 0
	v_pk_fma_f32 v[130:131], v[106:107], v[134:135], v[130:131]
	s_nop 0
	v_mul_f32_e32 v134, 0xbfb8aa3b, v130
	v_mul_f32_e32 v135, 0xbfb8aa3b, v131
	v_exp_f32_e32 v134, v134
	v_exp_f32_e32 v135, v135
	s_nop 0
	v_pk_add_f32 v[134:135], v[134:135], 1.0 op_sel_hi:[1,0]
	s_nop 0
	v_div_scale_f32 v138, s[2:3], v135, v135, 1.0
	v_rcp_f32_e32 v139, v138
	s_nop 0
	v_fma_f32 v142, -v138, v139, 1.0
	v_fmac_f32_e32 v139, v142, v139
	v_div_scale_f32 v142, vcc, 1.0, v135, 1.0
	v_mul_f32_e32 v143, v142, v139
	v_fma_f32 v150, -v138, v143, v142
	v_fmac_f32_e32 v143, v150, v139
	v_fma_f32 v138, -v138, v143, v142
	v_div_fmas_f32 v138, v138, v139, v143
	v_div_fixup_f32 v135, v138, v135, 1.0
	v_div_scale_f32 v138, s[2:3], v134, v134, 1.0
	v_rcp_f32_e32 v139, v138
	s_nop 0
	v_fma_f32 v142, -v138, v139, 1.0
	v_fmac_f32_e32 v139, v142, v139
	v_div_scale_f32 v142, vcc, 1.0, v134, 1.0
	v_mul_f32_e32 v143, v142, v139
	v_fma_f32 v150, -v138, v143, v142
	v_fmac_f32_e32 v143, v150, v139
	v_fma_f32 v138, -v138, v143, v142
	v_div_fmas_f32 v138, v138, v139, v143
	v_div_fixup_f32 v134, v138, v134, 1.0
	v_pk_mul_f32 v[130:131], v[130:131], v[134:135]
	v_mov_b32_dpp v142, v124 row_mirror row_mask:0xf bank_mask:0xf bound_ctrl:1
	v_mov_b32_dpp v150, v125 row_mirror row_mask:0xf bank_mask:0xf bound_ctrl:1
	v_pk_mul_f32 v[134:135], v[98:99], v[130:131]
	v_mov_b32_dpp v130, v108 row_shr:2 row_mask:0xf bank_mask:0xf bound_ctrl:1
	v_mov_b32_dpp v139, v142 quad_perm:[1,0,3,2] row_mask:0xf bank_mask:0xf bound_ctrl:1
	v_mov_b32_dpp v131, v109 row_shr:2 row_mask:0xf bank_mask:0xf bound_ctrl:1
	v_mov_b32_dpp v151, v150 quad_perm:[1,0,3,2] row_mask:0xf bank_mask:0xf bound_ctrl:1
	v_mov_b32_dpp v138, v108 row_shr:1 row_mask:0xf bank_mask:0xf bound_ctrl:1
	v_mov_b32_dpp v143, v109 row_shr:1 row_mask:0xf bank_mask:0xf bound_ctrl:1
	v_cndmask_b32_e64 v131, v131, v151, s[14:15]
	v_cndmask_b32_e64 v130, v130, v139, s[14:15]
	v_cndmask_b32_e64 v139, v143, v150, s[16:17]
	v_cndmask_b32_e64 v138, v138, v142, s[16:17]
	v_pk_fma_f32 v[130:131], v[132:133], v[130:131], v[144:145]
	s_nop 0
	v_pk_fma_f32 v[130:131], v[140:141], v[138:139], v[130:131]
	s_nop 0
	v_pk_fma_f32 v[130:131], v[108:109], v[136:137], v[130:131]
	s_nop 0
	v_mul_f32_e32 v132, 0xbfb8aa3b, v130
	v_mul_f32_e32 v133, 0xbfb8aa3b, v131
	v_exp_f32_e32 v132, v132
	v_exp_f32_e32 v133, v133
	s_nop 0
	v_pk_add_f32 v[132:133], v[132:133], 1.0 op_sel_hi:[1,0]
	s_nop 0
	v_div_scale_f32 v136, s[2:3], v133, v133, 1.0
	v_rcp_f32_e32 v137, v136
	s_nop 0
	v_fma_f32 v138, -v136, v137, 1.0
	v_fmac_f32_e32 v137, v138, v137
	v_div_scale_f32 v138, vcc, 1.0, v133, 1.0
	v_mul_f32_e32 v139, v138, v137
	v_fma_f32 v140, -v136, v139, v138
	v_fmac_f32_e32 v139, v140, v137
	v_fma_f32 v136, -v136, v139, v138
	v_div_fmas_f32 v136, v136, v137, v139
	v_div_fixup_f32 v133, v136, v133, 1.0
	v_div_scale_f32 v136, s[2:3], v132, v132, 1.0
	v_rcp_f32_e32 v137, v136
	s_nop 0
	v_fma_f32 v138, -v136, v137, 1.0
	v_fmac_f32_e32 v137, v138, v137
	v_div_scale_f32 v138, vcc, 1.0, v132, 1.0
	v_mul_f32_e32 v139, v138, v137
	v_fma_f32 v140, -v136, v139, v138
	v_fmac_f32_e32 v139, v140, v137
	v_fma_f32 v136, -v136, v139, v138
	v_div_fmas_f32 v136, v136, v137, v139
	v_div_fixup_f32 v132, v136, v132, 1.0
	v_pk_mul_f32 v[130:131], v[130:131], v[132:133]
	v_cvt_pk_bf16_f32 v132, v134, v135
	v_pk_mul_f32 v[136:137], v[100:101], v[130:131]
	v_or_b32_e32 v134, 16, v16
	v_cvt_pk_bf16_f32 v130, v146, v147
	v_cvt_pk_bf16_f32 v131, v148, v149
	v_cvt_pk_bf16_f32 v133, v136, v137
	v_mad_i64_i32 v[134:135], s[2:3], v134, s40, v[190:191]
	global_load_dwordx4 v[146:149], v[198:199], off
	s_nop 0
	global_load_dwordx4 v[150:153], v[196:197], off
	s_nop 0
	global_load_dwordx4 v[154:157], v[194:195], off
	s_nop 0
	global_load_dwordx4 v[158:161], v[192:193], off
	s_nop 0
	global_store_dwordx4 v[134:135], v[130:133], off
	s_nop 3
	global_load_dwordx4 v[130:133], v[198:199], off offset:16
	s_nop 0
	global_load_dwordx4 v[138:141], v[196:197], off offset:16
	s_nop 0
	global_load_dwordx4 v[134:137], v[194:195], off offset:16
	s_nop 0
	global_load_dwordx4 v[142:145], v[192:193], off offset:16
	s_nop 0
	s_waitcnt vmcnt(5)
; DI float sigmoidf_(float x) { return 1.f / (1.f + __expf(-x)); }
; DI void up_epilogue(const PRef& p, int l, const f32x4 (&acc)[2][2][4][2], int brow, int bcol, int wr, int wc, int fr, int fq, float* exch) {
;     ...
;       for (int n = 0; n < 2; ++n) {
;         const int c = cw0 + n * 4;
;         const float4 w0 = *reinterpret_cast<const float4*>(cwp + c), w1 = *reinterpret_cast<const float4*>(cwp + DFF + c);
;         const float4 w2 = *reinterpret_cast<const float4*>(cwp + 2 * DFF + c), bs = *reinterpret_cast<const float4*>(cbp + c);
;         const float w0a[4] = {w0.x, w0.y, w0.z, w0.w}, w1a[4] = {w1.x, w1.y, w1.z, w1.w}, w2a[4] = {w2.x, w2.y, w2.z, w2.w}, bsa[4] = {bs.x, bs.y, bs.z, bs.w};
;         float p62a[4] = {0.f, 0.f, 0.f, 0.f}, p63a[4] = {0.f, 0.f, 0.f, 0.f};
;         if (m == 0 && sp > 0) {
;           const float4 p62 = *reinterpret_cast<const float4*>(exch + (((sp - 1) * 2 + 0) * 128 + tc0 + n * 4));
;           const float4 p63 = *reinterpret_cast<const float4*>(exch + (((sp - 1) * 2 + 1) * 128 + tc0 + n * 4));
;           p62a[0] = p62.x; p62a[1] = p62.y; p62a[2] = p62.z; p62a[3] = p62.w;
;           p63a[0] = p63.x; p63a[1] = p63.y; p63a[2] = p63.z; p63a[3] = p63.w;
;         }
; #pragma unroll
;         for (int j = 0; j < 4; ++j) {
;           const float a = acc[ai][0][m][n][j], g = acc[ai][1][m][n][j];
;           float pr1 = dppz<0x111>(a), pr2 = dppz<0x112>(a);
;           if (m == 0) {
;             if (fr == 0) { pr1 = p63a[j]; pr2 = p62a[j]; }
;             if (fr == 1) { pr2 = p63a[j]; }
;           } else {
;             const float am = acc[ai][0][m > 0 ? m - 1 : 0][n][j];
;             const float mir = dppz<0x140>(am);
;             const float swp = dppz<0xB1>(mir);
;             if (fr == 0) { pr1 = mir; }
;             if (fr < 2) { pr2 = swp; }
;           }
;           const float cv = bsa[j] + w0a[j] * pr2 + w1a[j] * pr1 + w2a[j] * a;
;           o[n * 4 + j] = cv * sigmoidf_(cv) * g;
	v_pk_fma_f32 v[146:147], v[146:147], v[162:163], v[158:159]
	s_nop 0
	v_pk_fma_f32 v[146:147], v[150:151], v[164:165], v[146:147]
	v_mov_b32_dpp v165, v166 quad_perm:[1,0,3,2] row_mask:0xf bank_mask:0xf bound_ctrl:1
	v_pk_fma_f32 v[146:147], v[94:95], v[154:155], v[146:147]
	v_mov_b32_dpp v164, v78 row_shr:1 row_mask:0xf bank_mask:0xf bound_ctrl:1
	v_mul_f32_e32 v150, 0xbfb8aa3b, v146
	v_mul_f32_e32 v151, 0xbfb8aa3b, v147
	v_exp_f32_e32 v150, v150
	v_exp_f32_e32 v151, v151
	v_cndmask_b32_e64 v164, v164, v166, s[16:17]
	v_pk_add_f32 v[150:151], v[150:151], 1.0 op_sel_hi:[1,0]
	s_nop 0
	v_div_scale_f32 v154, s[2:3], v151, v151, 1.0
	v_rcp_f32_e32 v155, v154
	s_nop 0
	v_fma_f32 v158, -v154, v155, 1.0
	v_fmac_f32_e32 v155, v158, v155
	v_div_scale_f32 v158, vcc, 1.0, v151, 1.0
	v_mul_f32_e32 v159, v158, v155
	v_fma_f32 v162, -v154, v159, v158
	v_fmac_f32_e32 v159, v162, v155
	v_fma_f32 v154, -v154, v159, v158
	v_div_fmas_f32 v154, v154, v155, v159
	v_div_fixup_f32 v151, v154, v151, 1.0
	v_div_scale_f32 v154, s[2:3], v150, v150, 1.0
	v_rcp_f32_e32 v155, v154
	s_nop 0
	v_fma_f32 v158, -v154, v155, 1.0
	v_fmac_f32_e32 v155, v158, v155
	v_div_scale_f32 v158, vcc, 1.0, v150, 1.0
	v_mul_f32_e32 v159, v158, v155
	v_fma_f32 v162, -v154, v159, v158
	v_fmac_f32_e32 v159, v162, v155
	v_fma_f32 v154, -v154, v159, v158
	v_div_fmas_f32 v154, v154, v155, v159
	v_div_fixup_f32 v150, v154, v150, 1.0
	v_mov_b32_dpp v158, v112 row_mirror row_mask:0xf bank_mask:0xf bound_ctrl:1
	v_mov_b32_dpp v162, v113 row_mirror row_mask:0xf bank_mask:0xf bound_ctrl:1
	v_pk_mul_f32 v[146:147], v[146:147], v[150:151]
	v_mov_b32_dpp v150, v96 row_shr:2 row_mask:0xf bank_mask:0xf bound_ctrl:1
	v_mov_b32_dpp v155, v158 quad_perm:[1,0,3,2] row_mask:0xf bank_mask:0xf bound_ctrl:1
	v_mov_b32_dpp v151, v97 row_shr:2 row_mask:0xf bank_mask:0xf bound_ctrl:1
	v_mov_b32_dpp v163, v162 quad_perm:[1,0,3,2] row_mask:0xf bank_mask:0xf bound_ctrl:1
	v_mov_b32_dpp v154, v96 row_shr:1 row_mask:0xf bank_mask:0xf bound_ctrl:1
	v_mov_b32_dpp v159, v97 row_shr:1 row_mask:0xf bank_mask:0xf bound_ctrl:1
	v_cndmask_b32_e64 v151, v151, v163, s[14:15]
	v_cndmask_b32_e64 v150, v150, v155, s[14:15]
	v_cndmask_b32_e64 v155, v159, v162, s[16:17]
	v_cndmask_b32_e64 v154, v154, v158, s[16:17]
	v_pk_fma_f32 v[148:149], v[148:149], v[150:151], v[160:161]
	v_pk_mul_f32 v[146:147], v[86:87], v[146:147]
	v_pk_fma_f32 v[148:149], v[152:153], v[154:155], v[148:149]
	v_mov_b32_dpp v162, v78 row_shr:2 row_mask:0xf bank_mask:0xf bound_ctrl:1
	v_pk_fma_f32 v[148:149], v[96:97], v[156:157], v[148:149]
	v_mov_b32_dpp v163, v79 row_shr:2 row_mask:0xf bank_mask:0xf bound_ctrl:1
	v_mul_f32_e32 v150, 0xbfb8aa3b, v148
	v_mul_f32_e32 v151, 0xbfb8aa3b, v149
	v_exp_f32_e32 v150, v150
	v_exp_f32_e32 v151, v151
	v_cndmask_b32_e64 v163, v163, v169, s[14:15]
	v_cndmask_b32_e64 v162, v162, v165, s[14:15]
	v_cndmask_b32_e64 v165, v167, v168, s[16:17]
	v_pk_add_f32 v[150:151], v[150:151], 1.0 op_sel_hi:[1,0]
	s_nop 0
	v_div_scale_f32 v152, s[2:3], v151, v151, 1.0
	v_rcp_f32_e32 v153, v152
	s_nop 0
	v_fma_f32 v154, -v152, v153, 1.0
	v_fmac_f32_e32 v153, v154, v153
	v_div_scale_f32 v154, vcc, 1.0, v151, 1.0
	v_mul_f32_e32 v155, v154, v153
	v_fma_f32 v156, -v152, v155, v154
	v_fmac_f32_e32 v155, v156, v153
	v_fma_f32 v152, -v152, v155, v154
	v_div_fmas_f32 v152, v152, v153, v155
	v_div_fixup_f32 v151, v152, v151, 1.0
	v_div_scale_f32 v152, s[2:3], v150, v150, 1.0
	v_rcp_f32_e32 v153, v152
	s_nop 0
	v_fma_f32 v154, -v152, v153, 1.0
	v_fmac_f32_e32 v153, v154, v153
	v_div_scale_f32 v154, vcc, 1.0, v150, 1.0
	v_mul_f32_e32 v155, v154, v153
	v_fma_f32 v156, -v152, v155, v154
	v_fmac_f32_e32 v155, v156, v153
	v_fma_f32 v152, -v152, v155, v154
	v_div_fmas_f32 v152, v152, v153, v155
	v_div_fixup_f32 v150, v152, v150, 1.0
	v_mov_b32_dpp v154, v106 row_mirror row_mask:0xf bank_mask:0xf bound_ctrl:1
	v_mov_b32_dpp v156, v107 row_mirror row_mask:0xf bank_mask:0xf bound_ctrl:1
	v_pk_mul_f32 v[148:149], v[148:149], v[150:151]
	v_mov_b32_dpp v150, v90 row_shr:2 row_mask:0xf bank_mask:0xf bound_ctrl:1
	v_mov_b32_dpp v153, v154 quad_perm:[1,0,3,2] row_mask:0xf bank_mask:0xf bound_ctrl:1
	v_mov_b32_dpp v151, v91 row_shr:2 row_mask:0xf bank_mask:0xf bound_ctrl:1
	v_mov_b32_dpp v157, v156 quad_perm:[1,0,3,2] row_mask:0xf bank_mask:0xf bound_ctrl:1
	v_mov_b32_dpp v152, v90 row_shr:1 row_mask:0xf bank_mask:0xf bound_ctrl:1
	v_mov_b32_dpp v155, v91 row_shr:1 row_mask:0xf bank_mask:0xf bound_ctrl:1
	v_cndmask_b32_e64 v151, v151, v157, s[14:15]
	v_cndmask_b32_e64 v150, v150, v153, s[14:15]
	v_cndmask_b32_e64 v153, v155, v156, s[16:17]
	v_cndmask_b32_e64 v152, v152, v154, s[16:17]
	s_waitcnt vmcnt(0)
; DI unsigned pack2(float a, float b) { f32v2 v = {a, b}; return __builtin_bit_cast(unsigned, __builtin_convertvector(v, bf16v2)); }
; DI float sigmoidf_(float x) { return 1.f / (1.f + __expf(-x)); }
; DI void up_epilogue(const PRef& p, int l, const f32x4 (&acc)[2][2][4][2], int brow, int bcol, int wr, int wc, int fr, int fq, float* exch) {
;     ...
;       for (int n = 0; n < 2; ++n) {
;         const int c = cw0 + n * 4;
;         const float4 w0 = *reinterpret_cast<const float4*>(cwp + c), w1 = *reinterpret_cast<const float4*>(cwp + DFF + c);
;         const float4 w2 = *reinterpret_cast<const float4*>(cwp + 2 * DFF + c), bs = *reinterpret_cast<const float4*>(cbp + c);
;         const float w0a[4] = {w0.x, w0.y, w0.z, w0.w}, w1a[4] = {w1.x, w1.y, w1.z, w1.w}, w2a[4] = {w2.x, w2.y, w2.z, w2.w}, bsa[4] = {bs.x, bs.y, bs.z, bs.w};
;         float p62a[4] = {0.f, 0.f, 0.f, 0.f}, p63a[4] = {0.f, 0.f, 0.f, 0.f};
;         if (m == 0 && sp > 0) {
;           const float4 p62 = *reinterpret_cast<const float4*>(exch + (((sp - 1) * 2 + 0) * 128 + tc0 + n * 4));
;           const float4 p63 = *reinterpret_cast<const float4*>(exch + (((sp - 1) * 2 + 1) * 128 + tc0 + n * 4));
;           p62a[0] = p62.x; p62a[1] = p62.y; p62a[2] = p62.z; p62a[3] = p62.w;
;           p63a[0] = p63.x; p63a[1] = p63.y; p63a[2] = p63.z; p63a[3] = p63.w;
;         }
; #pragma unroll
;         for (int j = 0; j < 4; ++j) {
;           const float a = acc[ai][0][m][n][j], g = acc[ai][1][m][n][j];
;           float pr1 = dppz<0x111>(a), pr2 = dppz<0x112>(a);
;           if (m == 0) {
;             if (fr == 0) { pr1 = p63a[j]; pr2 = p62a[j]; }
;             if (fr == 1) { pr2 = p63a[j]; }
;           } else {
;             const float am = acc[ai][0][m > 0 ? m - 1 : 0][n][j];
;             const float mir = dppz<0x140>(am);
;             const float swp = dppz<0xB1>(mir);
;             if (fr == 0) { pr1 = mir; }
;             if (fr < 2) { pr2 = swp; }
;           }
;           const float cv = bsa[j] + w0a[j] * pr2 + w1a[j] * pr1 + w2a[j] * a;
;           o[n * 4 + j] = cv * sigmoidf_(cv) * g;
;         }
;       }
;       uint4 ov; ov.x = pack2(o[0], o[1]); ov.y = pack2(o[2], o[3]); ov.z = pack2(o[4], o[5]); ov.w = pack2(o[6], o[7]);
;       *reinterpret_cast<uint4*>(hmid + (size_t)(brow + ai * HALF + wr * 64 + m * 16 + fr) * DFF + cw0) = ov;
	v_pk_fma_f32 v[130:131], v[130:131], v[150:151], v[142:143]
	v_pk_mul_f32 v[148:149], v[88:89], v[148:149]
	v_pk_fma_f32 v[130:131], v[138:139], v[152:153], v[130:131]
	s_nop 0
	v_pk_fma_f32 v[130:131], v[90:91], v[134:135], v[130:131]
	s_nop 0
	v_mul_f32_e32 v134, 0xbfb8aa3b, v130
	v_mul_f32_e32 v135, 0xbfb8aa3b, v131
	v_exp_f32_e32 v134, v134
	v_exp_f32_e32 v135, v135
	s_nop 0
	v_pk_add_f32 v[134:135], v[134:135], 1.0 op_sel_hi:[1,0]
	s_nop 0
	v_div_scale_f32 v138, s[2:3], v135, v135, 1.0
	v_rcp_f32_e32 v139, v138
	s_nop 0
	v_fma_f32 v142, -v138, v139, 1.0
	v_fmac_f32_e32 v139, v142, v139
	v_div_scale_f32 v142, vcc, 1.0, v135, 1.0
	v_mul_f32_e32 v143, v142, v139
	v_fma_f32 v150, -v138, v143, v142
	v_fmac_f32_e32 v143, v150, v139
	v_fma_f32 v138, -v138, v143, v142
	v_div_fmas_f32 v138, v138, v139, v143
	v_div_fixup_f32 v135, v138, v135, 1.0
	v_div_scale_f32 v138, s[2:3], v134, v134, 1.0
	v_rcp_f32_e32 v139, v138
	s_nop 0
	v_fma_f32 v142, -v138, v139, 1.0
	v_fmac_f32_e32 v139, v142, v139
	v_div_scale_f32 v142, vcc, 1.0, v134, 1.0
	v_mul_f32_e32 v143, v142, v139
	v_fma_f32 v150, -v138, v143, v142
	v_fmac_f32_e32 v143, v150, v139
	v_fma_f32 v138, -v138, v143, v142
	v_div_fmas_f32 v138, v138, v139, v143
	v_div_fixup_f32 v134, v138, v134, 1.0
	v_pk_mul_f32 v[130:131], v[130:131], v[134:135]
	v_mov_b32_dpp v142, v108 row_mirror row_mask:0xf bank_mask:0xf bound_ctrl:1
	v_mov_b32_dpp v150, v109 row_mirror row_mask:0xf bank_mask:0xf bound_ctrl:1
	v_pk_mul_f32 v[134:135], v[82:83], v[130:131]
	v_mov_b32_dpp v130, v92 row_shr:2 row_mask:0xf bank_mask:0xf bound_ctrl:1
	v_mov_b32_dpp v139, v142 quad_perm:[1,0,3,2] row_mask:0xf bank_mask:0xf bound_ctrl:1
	v_mov_b32_dpp v131, v93 row_shr:2 row_mask:0xf bank_mask:0xf bound_ctrl:1
	v_mov_b32_dpp v151, v150 quad_perm:[1,0,3,2] row_mask:0xf bank_mask:0xf bound_ctrl:1
	v_mov_b32_dpp v138, v92 row_shr:1 row_mask:0xf bank_mask:0xf bound_ctrl:1
	v_mov_b32_dpp v143, v93 row_shr:1 row_mask:0xf bank_mask:0xf bound_ctrl:1
	v_cndmask_b32_e64 v131, v131, v151, s[14:15]
	v_cndmask_b32_e64 v130, v130, v139, s[14:15]
	v_cndmask_b32_e64 v139, v143, v150, s[16:17]
	v_cndmask_b32_e64 v138, v138, v142, s[16:17]
	v_pk_fma_f32 v[130:131], v[132:133], v[130:131], v[144:145]
	s_nop 0
	v_pk_fma_f32 v[130:131], v[140:141], v[138:139], v[130:131]
	s_nop 0
	v_pk_fma_f32 v[130:131], v[92:93], v[136:137], v[130:131]
	s_nop 0
	v_mul_f32_e32 v132, 0xbfb8aa3b, v130
	v_mul_f32_e32 v133, 0xbfb8aa3b, v131
	v_exp_f32_e32 v132, v132
	v_exp_f32_e32 v133, v133
	s_nop 0
	v_pk_add_f32 v[132:133], v[132:133], 1.0 op_sel_hi:[1,0]
	s_nop 0
	v_div_scale_f32 v136, s[2:3], v133, v133, 1.0
	v_rcp_f32_e32 v137, v136
	s_nop 0
	v_fma_f32 v138, -v136, v137, 1.0
	v_fmac_f32_e32 v137, v138, v137
	v_div_scale_f32 v138, vcc, 1.0, v133, 1.0
	v_mul_f32_e32 v139, v138, v137
	v_fma_f32 v140, -v136, v139, v138
	v_fmac_f32_e32 v139, v140, v137
	v_fma_f32 v136, -v136, v139, v138
	v_div_fmas_f32 v136, v136, v137, v139
	v_div_fixup_f32 v133, v136, v133, 1.0
	v_div_scale_f32 v136, s[2:3], v132, v132, 1.0
	v_rcp_f32_e32 v137, v136
	s_nop 0
	v_fma_f32 v138, -v136, v137, 1.0
	v_fmac_f32_e32 v137, v138, v137
	v_div_scale_f32 v138, vcc, 1.0, v132, 1.0
	v_mul_f32_e32 v139, v138, v137
	v_fma_f32 v140, -v136, v139, v138
	v_fmac_f32_e32 v139, v140, v137
	v_fma_f32 v136, -v136, v139, v138
	v_div_fmas_f32 v136, v136, v137, v139
	v_div_fixup_f32 v132, v136, v132, 1.0
	v_pk_mul_f32 v[130:131], v[130:131], v[132:133]
	v_cvt_pk_bf16_f32 v132, v134, v135
	v_pk_mul_f32 v[136:137], v[84:85], v[130:131]
	v_or_b32_e32 v134, 32, v16
	v_cvt_pk_bf16_f32 v130, v146, v147
	v_cvt_pk_bf16_f32 v131, v148, v149
	v_cvt_pk_bf16_f32 v133, v136, v137
	v_mad_i64_i32 v[134:135], s[2:3], v134, s40, v[190:191]
	global_load_dwordx4 v[146:149], v[198:199], off
	s_nop 0
	global_load_dwordx4 v[150:153], v[196:197], off
	s_nop 0
	global_load_dwordx4 v[154:157], v[194:195], off
	s_nop 0
	global_load_dwordx4 v[158:161], v[192:193], off
	s_nop 0
	global_store_dwordx4 v[134:135], v[130:133], off
	s_nop 3
	global_load_dwordx4 v[130:133], v[198:199], off offset:16
	s_nop 0
	global_load_dwordx4 v[138:141], v[196:197], off offset:16
	s_nop 0
	global_load_dwordx4 v[134:137], v[194:195], off offset:16
	s_nop 0
	global_load_dwordx4 v[142:145], v[192:193], off offset:16
	s_nop 0
	s_waitcnt vmcnt(5)
; DI float sigmoidf_(float x) { return 1.f / (1.f + __expf(-x)); }
; DI void up_epilogue(const PRef& p, int l, const f32x4 (&acc)[2][2][4][2], int brow, int bcol, int wr, int wc, int fr, int fq, float* exch) {
;     ...
;       for (int n = 0; n < 2; ++n) {
;         const int c = cw0 + n * 4;
;         const float4 w0 = *reinterpret_cast<const float4*>(cwp + c), w1 = *reinterpret_cast<const float4*>(cwp + DFF + c);
;         const float4 w2 = *reinterpret_cast<const float4*>(cwp + 2 * DFF + c), bs = *reinterpret_cast<const float4*>(cbp + c);
;         const float w0a[4] = {w0.x, w0.y, w0.z, w0.w}, w1a[4] = {w1.x, w1.y, w1.z, w1.w}, w2a[4] = {w2.x, w2.y, w2.z, w2.w}, bsa[4] = {bs.x, bs.y, bs.z, bs.w};
;         float p62a[4] = {0.f, 0.f, 0.f, 0.f}, p63a[4] = {0.f, 0.f, 0.f, 0.f};
;         if (m == 0 && sp > 0) {
;           const float4 p62 = *reinterpret_cast<const float4*>(exch + (((sp - 1) * 2 + 0) * 128 + tc0 + n * 4));
;           const float4 p63 = *reinterpret_cast<const float4*>(exch + (((sp - 1) * 2 + 1) * 128 + tc0 + n * 4));
;           p62a[0] = p62.x; p62a[1] = p62.y; p62a[2] = p62.z; p62a[3] = p62.w;
;           p63a[0] = p63.x; p63a[1] = p63.y; p63a[2] = p63.z; p63a[3] = p63.w;
;         }
; #pragma unroll
;         for (int j = 0; j < 4; ++j) {
;           const float a = acc[ai][0][m][n][j], g = acc[ai][1][m][n][j];
;           float pr1 = dppz<0x111>(a), pr2 = dppz<0x112>(a);
;           if (m == 0) {
;             if (fr == 0) { pr1 = p63a[j]; pr2 = p62a[j]; }
;             if (fr == 1) { pr2 = p63a[j]; }
;           } else {
;             const float am = acc[ai][0][m > 0 ? m - 1 : 0][n][j];
;             const float mir = dppz<0x140>(am);
;             const float swp = dppz<0xB1>(mir);
;             if (fr == 0) { pr1 = mir; }
;             if (fr < 2) { pr2 = swp; }
;           }
;           const float cv = bsa[j] + w0a[j] * pr2 + w1a[j] * pr1 + w2a[j] * a;
;           o[n * 4 + j] = cv * sigmoidf_(cv) * g;
	v_pk_fma_f32 v[146:147], v[146:147], v[162:163], v[158:159]
	s_nop 0
	v_pk_fma_f32 v[146:147], v[150:151], v[164:165], v[146:147]
	s_nop 0
	v_pk_fma_f32 v[146:147], v[78:79], v[154:155], v[146:147]
	s_nop 0
	v_mul_f32_e32 v150, 0xbfb8aa3b, v146
	v_mul_f32_e32 v151, 0xbfb8aa3b, v147
	v_exp_f32_e32 v150, v150
	v_exp_f32_e32 v151, v151
	s_nop 0
	v_pk_add_f32 v[150:151], v[150:151], 1.0 op_sel_hi:[1,0]
	s_nop 0
	v_div_scale_f32 v154, s[2:3], v151, v151, 1.0
	v_rcp_f32_e32 v155, v154
	s_nop 0
	v_fma_f32 v158, -v154, v155, 1.0
	v_fmac_f32_e32 v155, v158, v155
	v_div_scale_f32 v158, vcc, 1.0, v151, 1.0
	v_mul_f32_e32 v159, v158, v155
	v_fma_f32 v162, -v154, v159, v158
	v_fmac_f32_e32 v159, v162, v155
	v_fma_f32 v154, -v154, v159, v158
	v_div_fmas_f32 v154, v154, v155, v159
	v_div_fixup_f32 v151, v154, v151, 1.0
	v_div_scale_f32 v154, s[2:3], v150, v150, 1.0
	v_rcp_f32_e32 v155, v154
	s_nop 0
	v_fma_f32 v158, -v154, v155, 1.0
	v_fmac_f32_e32 v155, v158, v155
	v_div_scale_f32 v158, vcc, 1.0, v150, 1.0
	v_mul_f32_e32 v159, v158, v155
	v_fma_f32 v162, -v154, v159, v158
	v_fmac_f32_e32 v159, v162, v155
	v_fma_f32 v154, -v154, v159, v158
	v_div_fmas_f32 v154, v154, v155, v159
	v_div_fixup_f32 v150, v154, v150, 1.0
	v_mov_b32_dpp v158, v96 row_mirror row_mask:0xf bank_mask:0xf bound_ctrl:1
	v_mov_b32_dpp v162, v97 row_mirror row_mask:0xf bank_mask:0xf bound_ctrl:1
	v_pk_mul_f32 v[146:147], v[146:147], v[150:151]
	v_mov_b32_dpp v150, v80 row_shr:2 row_mask:0xf bank_mask:0xf bound_ctrl:1
	v_mov_b32_dpp v155, v158 quad_perm:[1,0,3,2] row_mask:0xf bank_mask:0xf bound_ctrl:1
	v_mov_b32_dpp v151, v81 row_shr:2 row_mask:0xf bank_mask:0xf bound_ctrl:1
	v_mov_b32_dpp v163, v162 quad_perm:[1,0,3,2] row_mask:0xf bank_mask:0xf bound_ctrl:1
	v_mov_b32_dpp v154, v80 row_shr:1 row_mask:0xf bank_mask:0xf bound_ctrl:1
	v_mov_b32_dpp v159, v81 row_shr:1 row_mask:0xf bank_mask:0xf bound_ctrl:1
	v_cndmask_b32_e64 v151, v151, v163, s[14:15]
	v_cndmask_b32_e64 v150, v150, v155, s[14:15]
	v_cndmask_b32_e64 v155, v159, v162, s[16:17]
	v_cndmask_b32_e64 v154, v154, v158, s[16:17]
	v_pk_fma_f32 v[148:149], v[148:149], v[150:151], v[160:161]
	v_pk_mul_f32 v[146:147], v[70:71], v[146:147]
	v_pk_fma_f32 v[148:149], v[152:153], v[154:155], v[148:149]
	s_nop 0
	v_pk_fma_f32 v[148:149], v[80:81], v[156:157], v[148:149]
	s_nop 0
	v_mul_f32_e32 v150, 0xbfb8aa3b, v148
	v_mul_f32_e32 v151, 0xbfb8aa3b, v149
	v_exp_f32_e32 v150, v150
	v_exp_f32_e32 v151, v151
	s_nop 0
	v_pk_add_f32 v[150:151], v[150:151], 1.0 op_sel_hi:[1,0]
	s_nop 0
	v_div_scale_f32 v152, s[2:3], v151, v151, 1.0
	v_rcp_f32_e32 v153, v152
	s_nop 0
	v_fma_f32 v154, -v152, v153, 1.0
	v_fmac_f32_e32 v153, v154, v153
	v_div_scale_f32 v154, vcc, 1.0, v151, 1.0
	v_mul_f32_e32 v155, v154, v153
	v_fma_f32 v156, -v152, v155, v154
	v_fmac_f32_e32 v155, v156, v153
	v_fma_f32 v152, -v152, v155, v154
	v_div_fmas_f32 v152, v152, v153, v155
	v_div_fixup_f32 v151, v152, v151, 1.0
	v_div_scale_f32 v152, s[2:3], v150, v150, 1.0
	v_rcp_f32_e32 v153, v152
	s_nop 0
	v_fma_f32 v154, -v152, v153, 1.0
	v_fmac_f32_e32 v153, v154, v153
	v_div_scale_f32 v154, vcc, 1.0, v150, 1.0
	v_mul_f32_e32 v155, v154, v153
	v_fma_f32 v156, -v152, v155, v154
	v_fmac_f32_e32 v155, v156, v153
	v_fma_f32 v152, -v152, v155, v154
	v_div_fmas_f32 v152, v152, v153, v155
	v_div_fixup_f32 v150, v152, v150, 1.0
	v_mov_b32_dpp v154, v90 row_mirror row_mask:0xf bank_mask:0xf bound_ctrl:1
	v_mov_b32_dpp v156, v91 row_mirror row_mask:0xf bank_mask:0xf bound_ctrl:1
	v_pk_mul_f32 v[148:149], v[148:149], v[150:151]
	v_mov_b32_dpp v150, v74 row_shr:2 row_mask:0xf bank_mask:0xf bound_ctrl:1
	v_mov_b32_dpp v153, v154 quad_perm:[1,0,3,2] row_mask:0xf bank_mask:0xf bound_ctrl:1
	v_mov_b32_dpp v151, v75 row_shr:2 row_mask:0xf bank_mask:0xf bound_ctrl:1
	v_mov_b32_dpp v157, v156 quad_perm:[1,0,3,2] row_mask:0xf bank_mask:0xf bound_ctrl:1
	v_mov_b32_dpp v152, v74 row_shr:1 row_mask:0xf bank_mask:0xf bound_ctrl:1
	v_mov_b32_dpp v155, v75 row_shr:1 row_mask:0xf bank_mask:0xf bound_ctrl:1
	v_cndmask_b32_e64 v151, v151, v157, s[14:15]
	v_cndmask_b32_e64 v150, v150, v153, s[14:15]
	v_cndmask_b32_e64 v153, v155, v156, s[16:17]
	v_cndmask_b32_e64 v152, v152, v154, s[16:17]
	s_waitcnt vmcnt(0)
; DI unsigned pack2(float a, float b) { f32v2 v = {a, b}; return __builtin_bit_cast(unsigned, __builtin_convertvector(v, bf16v2)); }
; DI float sigmoidf_(float x) { return 1.f / (1.f + __expf(-x)); }
; DI void up_epilogue(const PRef& p, int l, const f32x4 (&acc)[2][2][4][2], int brow, int bcol, int wr, int wc, int fr, int fq, float* exch) {
;     ...
;       for (int n = 0; n < 2; ++n) {
;         const int c = cw0 + n * 4;
;         const float4 w0 = *reinterpret_cast<const float4*>(cwp + c), w1 = *reinterpret_cast<const float4*>(cwp + DFF + c);
;         const float4 w2 = *reinterpret_cast<const float4*>(cwp + 2 * DFF + c), bs = *reinterpret_cast<const float4*>(cbp + c);
;         const float w0a[4] = {w0.x, w0.y, w0.z, w0.w}, w1a[4] = {w1.x, w1.y, w1.z, w1.w}, w2a[4] = {w2.x, w2.y, w2.z, w2.w}, bsa[4] = {bs.x, bs.y, bs.z, bs.w};
;         float p62a[4] = {0.f, 0.f, 0.f, 0.f}, p63a[4] = {0.f, 0.f, 0.f, 0.f};
;         if (m == 0 && sp > 0) {
;           const float4 p62 = *reinterpret_cast<const float4*>(exch + (((sp - 1) * 2 + 0) * 128 + tc0 + n * 4));
;           const float4 p63 = *reinterpret_cast<const float4*>(exch + (((sp - 1) * 2 + 1) * 128 + tc0 + n * 4));
;           p62a[0] = p62.x; p62a[1] = p62.y; p62a[2] = p62.z; p62a[3] = p62.w;
;           p63a[0] = p63.x; p63a[1] = p63.y; p63a[2] = p63.z; p63a[3] = p63.w;
;         }
; #pragma unroll
;         for (int j = 0; j < 4; ++j) {
;           const float a = acc[ai][0][m][n][j], g = acc[ai][1][m][n][j];
;           float pr1 = dppz<0x111>(a), pr2 = dppz<0x112>(a);
;           if (m == 0) {
;             if (fr == 0) { pr1 = p63a[j]; pr2 = p62a[j]; }
;             if (fr == 1) { pr2 = p63a[j]; }
;           } else {
;             const float am = acc[ai][0][m > 0 ? m - 1 : 0][n][j];
;             const float mir = dppz<0x140>(am);
;             const float swp = dppz<0xB1>(mir);
;             if (fr == 0) { pr1 = mir; }
;             if (fr < 2) { pr2 = swp; }
;           }
;           const float cv = bsa[j] + w0a[j] * pr2 + w1a[j] * pr1 + w2a[j] * a;
;           o[n * 4 + j] = cv * sigmoidf_(cv) * g;
;         }
;       }
;       uint4 ov; ov.x = pack2(o[0], o[1]); ov.y = pack2(o[2], o[3]); ov.z = pack2(o[4], o[5]); ov.w = pack2(o[6], o[7]);
;       *reinterpret_cast<uint4*>(hmid + (size_t)(brow + ai * HALF + wr * 64 + m * 16 + fr) * DFF + cw0) = ov;
	v_pk_fma_f32 v[130:131], v[130:131], v[150:151], v[142:143]
	v_pk_mul_f32 v[148:149], v[72:73], v[148:149]
	v_pk_fma_f32 v[130:131], v[138:139], v[152:153], v[130:131]
	s_nop 0
	v_pk_fma_f32 v[130:131], v[74:75], v[134:135], v[130:131]
	s_nop 0
	v_mul_f32_e32 v134, 0xbfb8aa3b, v130
	v_mul_f32_e32 v135, 0xbfb8aa3b, v131
	v_exp_f32_e32 v134, v134
	v_exp_f32_e32 v135, v135
	s_nop 0
	v_pk_add_f32 v[134:135], v[134:135], 1.0 op_sel_hi:[1,0]
	s_nop 0
	v_div_scale_f32 v138, s[2:3], v135, v135, 1.0
	v_rcp_f32_e32 v139, v138
	s_nop 0
	v_fma_f32 v142, -v138, v139, 1.0
	v_fmac_f32_e32 v139, v142, v139
	v_div_scale_f32 v142, vcc, 1.0, v135, 1.0
	v_mul_f32_e32 v143, v142, v139
	v_fma_f32 v150, -v138, v143, v142
	v_fmac_f32_e32 v143, v150, v139
	v_fma_f32 v138, -v138, v143, v142
	v_div_fmas_f32 v138, v138, v139, v143
	v_div_fixup_f32 v135, v138, v135, 1.0
	v_div_scale_f32 v138, s[2:3], v134, v134, 1.0
	v_rcp_f32_e32 v139, v138
	s_nop 0
	v_fma_f32 v142, -v138, v139, 1.0
	v_fmac_f32_e32 v139, v142, v139
	v_div_scale_f32 v142, vcc, 1.0, v134, 1.0
	v_mul_f32_e32 v143, v142, v139
	v_fma_f32 v150, -v138, v143, v142
	v_fmac_f32_e32 v143, v150, v139
	v_fma_f32 v138, -v138, v143, v142
	v_div_fmas_f32 v138, v138, v139, v143
	v_div_fixup_f32 v134, v138, v134, 1.0
	v_pk_mul_f32 v[130:131], v[130:131], v[134:135]
	v_mov_b32_dpp v142, v92 row_mirror row_mask:0xf bank_mask:0xf bound_ctrl:1
	v_mov_b32_dpp v150, v93 row_mirror row_mask:0xf bank_mask:0xf bound_ctrl:1
	v_pk_mul_f32 v[134:135], v[66:67], v[130:131]
	v_mov_b32_dpp v130, v76 row_shr:2 row_mask:0xf bank_mask:0xf bound_ctrl:1
	v_mov_b32_dpp v139, v142 quad_perm:[1,0,3,2] row_mask:0xf bank_mask:0xf bound_ctrl:1
	v_mov_b32_dpp v131, v77 row_shr:2 row_mask:0xf bank_mask:0xf bound_ctrl:1
	v_mov_b32_dpp v151, v150 quad_perm:[1,0,3,2] row_mask:0xf bank_mask:0xf bound_ctrl:1
	v_mov_b32_dpp v138, v76 row_shr:1 row_mask:0xf bank_mask:0xf bound_ctrl:1
	v_mov_b32_dpp v143, v77 row_shr:1 row_mask:0xf bank_mask:0xf bound_ctrl:1
	v_cndmask_b32_e64 v131, v131, v151, s[14:15]
	v_cndmask_b32_e64 v130, v130, v139, s[14:15]
	v_cndmask_b32_e64 v139, v143, v150, s[16:17]
	v_cndmask_b32_e64 v138, v138, v142, s[16:17]
	v_pk_fma_f32 v[130:131], v[132:133], v[130:131], v[144:145]
	s_nop 0
	v_pk_fma_f32 v[130:131], v[140:141], v[138:139], v[130:131]
	s_nop 0
	v_pk_fma_f32 v[130:131], v[76:77], v[136:137], v[130:131]
	s_nop 0
	v_mul_f32_e32 v132, 0xbfb8aa3b, v130
	v_mul_f32_e32 v133, 0xbfb8aa3b, v131
	v_exp_f32_e32 v132, v132
	v_exp_f32_e32 v133, v133
	s_nop 0
	v_pk_add_f32 v[132:133], v[132:133], 1.0 op_sel_hi:[1,0]
	s_nop 0
	v_div_scale_f32 v136, s[2:3], v133, v133, 1.0
	v_rcp_f32_e32 v137, v136
	s_nop 0
	v_fma_f32 v138, -v136, v137, 1.0
	v_fmac_f32_e32 v137, v138, v137
	v_div_scale_f32 v138, vcc, 1.0, v133, 1.0
	v_mul_f32_e32 v139, v138, v137
	v_fma_f32 v140, -v136, v139, v138
	v_fmac_f32_e32 v139, v140, v137
	v_fma_f32 v136, -v136, v139, v138
	v_div_fmas_f32 v136, v136, v137, v139
	v_div_fixup_f32 v133, v136, v133, 1.0
	v_div_scale_f32 v136, s[2:3], v132, v132, 1.0
	v_rcp_f32_e32 v137, v136
	s_nop 0
	v_fma_f32 v138, -v136, v137, 1.0
	v_fmac_f32_e32 v137, v138, v137
	v_div_scale_f32 v138, vcc, 1.0, v132, 1.0
	v_mul_f32_e32 v139, v138, v137
	v_fma_f32 v140, -v136, v139, v138
	v_fmac_f32_e32 v139, v140, v137
	v_fma_f32 v136, -v136, v139, v138
	v_div_fmas_f32 v136, v136, v137, v139
	v_div_fixup_f32 v132, v136, v132, 1.0
	v_pk_mul_f32 v[130:131], v[130:131], v[132:133]
	v_cvt_pk_bf16_f32 v132, v134, v135
	v_pk_mul_f32 v[136:137], v[68:69], v[130:131]
	v_or_b32_e32 v134, 48, v16
	v_cvt_pk_bf16_f32 v130, v146, v147
	v_cvt_pk_bf16_f32 v131, v148, v149
	v_cvt_pk_bf16_f32 v133, v136, v137
	v_mad_i64_i32 v[134:135], s[2:3], v134, s40, v[190:191]
	global_load_dwordx4 v[162:165], v[198:199], off
	s_nop 0
	global_load_dwordx4 v[154:157], v[196:197], off
	s_nop 0
	global_load_dwordx4 v[158:161], v[194:195], off
	s_nop 0
	global_load_dwordx4 v[166:169], v[192:193], off
	s_nop 0
	global_store_dwordx4 v[134:135], v[130:133], off
	s_nop 3
	v_mov_b32_e32 v130, 0
	s_mov_b64 s[2:3], exec
	v_readlane_b32 s24, v254, 31
	v_readlane_b32 s25, v254, 32
	s_and_b64 s[24:25], s[2:3], s[24:25]
	s_mov_b64 exec, s[24:25]
	s_cbranch_execz .LBB0_1046
	ds_read_b128 v[170:173], v208 offset:1024
	ds_read_b128 v[174:177], v208 offset:1536

; DI float sigmoidf_(float x) { return 1.f / (1.f + __expf(-x)); }
; DI void up_epilogue(const PRef& p, int l, const f32x4 (&acc)[2][2][4][2], int brow, int bcol, int wr, int wc, int fr, int fq, float* exch) {
;     ...
;         if (m == 0 && sp > 0) {
;           const float4 p62 = *reinterpret_cast<const float4*>(exch + (((sp - 1) * 2 + 0) * 128 + tc0 + n * 4));
;           const float4 p63 = *reinterpret_cast<const float4*>(exch + (((sp - 1) * 2 + 1) * 128 + tc0 + n * 4));
;           p62a[0] = p62.x; p62a[1] = p62.y; p62a[2] = p62.z; p62a[3] = p62.w;
;           p63a[0] = p63.x; p63a[1] = p63.y; p63a[2] = p63.z; p63a[3] = p63.w;
;         }
; #pragma unroll
;         for (int j = 0; j < 4; ++j) {
;           const float a = acc[ai][0][m][n][j], g = acc[ai][1][m][n][j];
;           float pr1 = dppz<0x111>(a), pr2 = dppz<0x112>(a);
;           if (m == 0) {
;             if (fr == 0) { pr1 = p63a[j]; pr2 = p62a[j]; }
;             if (fr == 1) { pr2 = p63a[j]; }
;           } else {
;             const float am = acc[ai][0][m > 0 ? m - 1 : 0][n][j];
;             const float mir = dppz<0x140>(am);
;             const float swp = dppz<0xB1>(mir);
;             if (fr == 0) { pr1 = mir; }
;             if (fr < 2) { pr2 = swp; }
;           }
;           const float cv = bsa[j] + w0a[j] * pr2 + w1a[j] * pr1 + w2a[j] * a;
;           o[n * 4 + j] = cv * sigmoidf_(cv) * g;
.LBB0_1048:
	s_or_b64 exec, exec, s[2:3]
	s_waitcnt lgkmcnt(1)
	v_cndmask_b32_e64 v173, v217, v173, s[16:17]
	v_cndmask_b32_e64 v172, v216, v172, s[16:17]
	s_waitcnt lgkmcnt(0)
	v_cndmask_b32_e64 v172, v172, v176, s[18:19]
	v_cndmask_b32_e64 v173, v173, v177, s[18:19]
	s_waitcnt vmcnt(5)
	v_pk_fma_f32 v[164:165], v[164:165], v[172:173], v[168:169]
	v_cndmask_b32_e64 v168, v214, v176, s[16:17]
	v_cndmask_b32_e64 v169, v215, v177, s[16:17]
	v_pk_fma_f32 v[156:157], v[156:157], v[168:169], v[164:165]
	v_mov_b32_dpp v216, v31 row_mirror row_mask:0xf bank_mask:0xf bound_ctrl:1
	v_pk_fma_f32 v[156:157], v[64:65], v[160:161], v[156:157]
	v_mov_b32_dpp v215, v13 row_shr:2 row_mask:0xf bank_mask:0xf bound_ctrl:1
	v_mul_f32_e32 v160, 0xbfb8aa3b, v156
	v_mul_f32_e32 v161, 0xbfb8aa3b, v157
	v_exp_f32_e32 v160, v160
	v_exp_f32_e32 v161, v161
	v_mov_b32_dpp v217, v216 quad_perm:[1,0,3,2] row_mask:0xf bank_mask:0xf bound_ctrl:1
	v_mov_b32_dpp v214, v13 row_shr:1 row_mask:0xf bank_mask:0xf bound_ctrl:1
	v_mov_b32_dpp v220, v32 row_mirror row_mask:0xf bank_mask:0xf bound_ctrl:1
	v_pk_add_f32 v[160:161], v[160:161], 1.0 op_sel_hi:[1,0]
	v_mov_b32_dpp v224, v33 row_mirror row_mask:0xf bank_mask:0xf bound_ctrl:1
	v_div_scale_f32 v164, s[2:3], v161, v161, 1.0
	v_rcp_f32_e32 v165, v164
	v_mov_b32_dpp v219, v14 row_shr:2 row_mask:0xf bank_mask:0xf bound_ctrl:1
	v_mov_b32_dpp v221, v220 quad_perm:[1,0,3,2] row_mask:0xf bank_mask:0xf bound_ctrl:1
	v_mov_b32_dpp v223, v15 row_shr:2 row_mask:0xf bank_mask:0xf bound_ctrl:1
	v_fma_f32 v168, -v164, v165, 1.0
	v_fmac_f32_e32 v165, v168, v165
	v_div_scale_f32 v168, vcc, 1.0, v161, 1.0
	v_mul_f32_e32 v169, v168, v165
	v_fma_f32 v172, -v164, v169, v168
	v_fmac_f32_e32 v169, v172, v165
	v_fma_f32 v164, -v164, v169, v168
	v_div_fmas_f32 v164, v164, v165, v169
	v_div_fixup_f32 v161, v164, v161, 1.0
	v_div_scale_f32 v164, s[2:3], v160, v160, 1.0
	v_rcp_f32_e32 v165, v164
	v_mov_b32_dpp v225, v224 quad_perm:[1,0,3,2] row_mask:0xf bank_mask:0xf bound_ctrl:1
	v_mov_b32_dpp v218, v14 row_shr:1 row_mask:0xf bank_mask:0xf bound_ctrl:1
	v_mov_b32_dpp v222, v15 row_shr:1 row_mask:0xf bank_mask:0xf bound_ctrl:1
	v_fma_f32 v168, -v164, v165, 1.0
	v_fmac_f32_e32 v165, v168, v165
	v_div_scale_f32 v168, vcc, 1.0, v160, 1.0
	v_mul_f32_e32 v169, v168, v165
	v_fma_f32 v172, -v164, v169, v168
	v_fmac_f32_e32 v169, v172, v165
	v_fma_f32 v164, -v164, v169, v168
	v_div_fmas_f32 v164, v164, v165, v169
	v_div_fixup_f32 v160, v164, v160, 1.0
	v_pk_mul_f32 v[156:157], v[156:157], v[160:161]
	v_cndmask_b32_e64 v161, v203, v171, s[16:17]
	v_cndmask_b32_e64 v160, v202, v170, s[16:17]
	v_cndmask_b32_e64 v160, v160, v174, s[18:19]
	v_cndmask_b32_e64 v161, v161, v175, s[18:19]
	v_pk_fma_f32 v[160:161], v[162:163], v[160:161], v[166:167]
	v_cndmask_b32_e64 v162, v200, v174, s[16:17]
	v_cndmask_b32_e64 v163, v201, v175, s[16:17]
	v_pk_fma_f32 v[154:155], v[154:155], v[162:163], v[160:161]
	v_pk_mul_f32 v[156:157], v[56:57], v[156:157]
	v_pk_fma_f32 v[154:155], v[62:63], v[158:159], v[154:155]
	v_mov_b32_dpp v166, v62 row_mirror row_mask:0xf bank_mask:0xf bound_ctrl:1
	v_mul_f32_e32 v158, 0xbfb8aa3b, v154
	v_mul_f32_e32 v159, 0xbfb8aa3b, v155
	v_exp_f32_e32 v158, v158
	v_exp_f32_e32 v159, v159
	v_mov_b32_dpp v168, v63 row_mirror row_mask:0xf bank_mask:0xf bound_ctrl:1
	v_mov_b32_dpp v165, v166 quad_perm:[1,0,3,2] row_mask:0xf bank_mask:0xf bound_ctrl:1
	v_mov_b32_dpp v167, v47 row_shr:1 row_mask:0xf bank_mask:0xf bound_ctrl:1
	v_pk_add_f32 v[158:159], v[158:159], 1.0 op_sel_hi:[1,0]
	v_mov_b32_dpp v169, v168 quad_perm:[1,0,3,2] row_mask:0xf bank_mask:0xf bound_ctrl:1
	v_div_scale_f32 v160, s[2:3], v159, v159, 1.0
	v_rcp_f32_e32 v161, v160
	v_mov_b32_dpp v202, v30 row_mirror row_mask:0xf bank_mask:0xf bound_ctrl:1
	v_mov_b32_dpp v201, v12 row_shr:2 row_mask:0xf bank_mask:0xf bound_ctrl:1
	v_mov_b32_dpp v200, v12 row_shr:1 row_mask:0xf bank_mask:0xf bound_ctrl:1
	v_fma_f32 v162, -v160, v161, 1.0
	v_fmac_f32_e32 v161, v162, v161
	v_div_scale_f32 v162, vcc, 1.0, v159, 1.0
	v_mul_f32_e32 v163, v162, v161
	v_fma_f32 v164, -v160, v163, v162
	v_fmac_f32_e32 v163, v164, v161
	v_fma_f32 v160, -v160, v163, v162
	v_div_fmas_f32 v160, v160, v161, v163
	v_div_fixup_f32 v159, v160, v159, 1.0
	v_div_scale_f32 v160, s[2:3], v158, v158, 1.0
	v_rcp_f32_e32 v161, v160
	v_mov_b32_dpp v203, v202 quad_perm:[1,0,3,2] row_mask:0xf bank_mask:0xf bound_ctrl:1
	v_mov_b32_dpp v171, v26 row_mirror row_mask:0xf bank_mask:0xf bound_ctrl:1
	v_mov_b32_dpp v174, v27 row_mirror row_mask:0xf bank_mask:0xf bound_ctrl:1
	v_fma_f32 v162, -v160, v161, 1.0
	v_fmac_f32_e32 v161, v162, v161
	v_div_scale_f32 v162, vcc, 1.0, v158, 1.0
	v_mul_f32_e32 v163, v162, v161
	v_fma_f32 v164, -v160, v163, v162
	v_fmac_f32_e32 v163, v164, v161
	v_fma_f32 v160, -v160, v163, v162
	v_div_fmas_f32 v160, v160, v161, v163
	v_div_fixup_f32 v158, v160, v158, 1.0
	v_mov_b32_dpp v162, v59 row_shr:2 row_mask:0xf bank_mask:0xf bound_ctrl:1
	v_mov_b32_dpp v160, v58 row_shr:2 row_mask:0xf bank_mask:0xf bound_ctrl:1
	v_cndmask_b32_e64 v130, v160, v130, s[16:17]
	v_cndmask_b32_e64 v131, v162, v131, s[16:17]
	v_pk_mul_f32 v[154:155], v[154:155], v[158:159]
	v_mov_b32_dpp v159, v58 row_shr:1 row_mask:0xf bank_mask:0xf bound_ctrl:1
	v_mov_b32_dpp v161, v59 row_shr:1 row_mask:0xf bank_mask:0xf bound_ctrl:1
	v_cndmask_b32_e64 v131, v131, v151, s[18:19]
	v_cndmask_b32_e64 v130, v130, v150, s[18:19]
	v_cndmask_b32_e64 v151, v161, v151, s[16:17]
	v_cndmask_b32_e64 v150, v159, v150, s[16:17]
	s_waitcnt vmcnt(0)
; DI unsigned pack2(float a, float b) { f32v2 v = {a, b}; return __builtin_bit_cast(unsigned, __builtin_convertvector(v, bf16v2)); }
; DI float sigmoidf_(float x) { return 1.f / (1.f + __expf(-x)); }
; DI void up_epilogue(const PRef& p, int l, const f32x4 (&acc)[2][2][4][2], int brow, int bcol, int wr, int wc, int fr, int fq, float* exch) {
;     ...
;       for (int n = 0; n < 2; ++n) {
;         const int c = cw0 + n * 4;
;         const float4 w0 = *reinterpret_cast<const float4*>(cwp + c), w1 = *reinterpret_cast<const float4*>(cwp + DFF + c);
;         const float4 w2 = *reinterpret_cast<const float4*>(cwp + 2 * DFF + c), bs = *reinterpret_cast<const float4*>(cbp + c);
;         const float w0a[4] = {w0.x, w0.y, w0.z, w0.w}, w1a[4] = {w1.x, w1.y, w1.z, w1.w}, w2a[4] = {w2.x, w2.y, w2.z, w2.w}, bsa[4] = {bs.x, bs.y, bs.z, bs.w};
;         float p62a[4] = {0.f, 0.f, 0.f, 0.f}, p63a[4] = {0.f, 0.f, 0.f, 0.f};
;         if (m == 0 && sp > 0) {
;           const float4 p62 = *reinterpret_cast<const float4*>(exch + (((sp - 1) * 2 + 0) * 128 + tc0 + n * 4));
;           const float4 p63 = *reinterpret_cast<const float4*>(exch + (((sp - 1) * 2 + 1) * 128 + tc0 + n * 4));
;           p62a[0] = p62.x; p62a[1] = p62.y; p62a[2] = p62.z; p62a[3] = p62.w;
;           p63a[0] = p63.x; p63a[1] = p63.y; p63a[2] = p63.z; p63a[3] = p63.w;
;         }
; #pragma unroll
;         for (int j = 0; j < 4; ++j) {
;           const float a = acc[ai][0][m][n][j], g = acc[ai][1][m][n][j];
;           float pr1 = dppz<0x111>(a), pr2 = dppz<0x112>(a);
;           if (m == 0) {
;             if (fr == 0) { pr1 = p63a[j]; pr2 = p62a[j]; }
;             if (fr == 1) { pr2 = p63a[j]; }
;           } else {
;             const float am = acc[ai][0][m > 0 ? m - 1 : 0][n][j];
;             const float mir = dppz<0x140>(am);
;             const float swp = dppz<0xB1>(mir);
;             if (fr == 0) { pr1 = mir; }
;             if (fr < 2) { pr2 = swp; }
;           }
;           const float cv = bsa[j] + w0a[j] * pr2 + w1a[j] * pr1 + w2a[j] * a;
;           o[n * 4 + j] = cv * sigmoidf_(cv) * g;
;         }
;       }
;       uint4 ov; ov.x = pack2(o[0], o[1]); ov.y = pack2(o[2], o[3]); ov.z = pack2(o[4], o[5]); ov.w = pack2(o[6], o[7]);
;       *reinterpret_cast<uint4*>(hmid + (size_t)(brow + ai * HALF + wr * 64 + m * 16 + fr) * DFF + cw0) = ov;
	v_pk_fma_f32 v[130:131], v[138:139], v[130:131], v[146:147]
	v_pk_mul_f32 v[154:155], v[54:55], v[154:155]
	v_pk_fma_f32 v[130:131], v[142:143], v[150:151], v[130:131]
	v_add_u32_e32 v158, 0x80, v16
	v_pk_fma_f32 v[130:131], v[58:59], v[134:135], v[130:131]
	v_mov_b32_dpp v162, v46 row_shr:2 row_mask:0xf bank_mask:0xf bound_ctrl:1
	v_mul_f32_e32 v134, 0xbfb8aa3b, v130
	v_mul_f32_e32 v135, 0xbfb8aa3b, v131
	v_exp_f32_e32 v134, v134
	v_exp_f32_e32 v135, v135
	v_mov_b32_dpp v163, v47 row_shr:2 row_mask:0xf bank_mask:0xf bound_ctrl:1
	v_mov_b32_dpp v164, v46 row_shr:1 row_mask:0xf bank_mask:0xf bound_ctrl:1
	v_cndmask_b32_e64 v163, v163, v169, s[14:15]
	v_pk_add_f32 v[134:135], v[134:135], 1.0 op_sel_hi:[1,0]
	v_cndmask_b32_e64 v162, v162, v165, s[14:15]
	v_div_scale_f32 v138, s[2:3], v135, v135, 1.0
	v_rcp_f32_e32 v139, v138
	v_cndmask_b32_e64 v165, v167, v168, s[16:17]
	v_cndmask_b32_e64 v164, v164, v166, s[16:17]
	v_mov_b32_dpp v166, v46 row_mirror row_mask:0xf bank_mask:0xf bound_ctrl:1
	v_fma_f32 v142, -v138, v139, 1.0
	v_fmac_f32_e32 v139, v142, v139
	v_div_scale_f32 v142, vcc, 1.0, v135, 1.0
	v_mul_f32_e32 v143, v142, v139
	v_fma_f32 v146, -v138, v143, v142
	v_fmac_f32_e32 v143, v146, v139
	v_fma_f32 v138, -v138, v143, v142
	v_div_fmas_f32 v138, v138, v139, v143
	v_div_fixup_f32 v135, v138, v135, 1.0
	v_div_scale_f32 v138, s[2:3], v134, v134, 1.0
	v_rcp_f32_e32 v139, v138
	v_mov_b32_dpp v168, v47 row_mirror row_mask:0xf bank_mask:0xf bound_ctrl:1
	v_mov_b32_dpp v167, v31 row_shr:1 row_mask:0xf bank_mask:0xf bound_ctrl:1
	v_mov_b32_dpp v173, v8 row_shr:2 row_mask:0xf bank_mask:0xf bound_ctrl:1
	v_fma_f32 v142, -v138, v139, 1.0
	v_fmac_f32_e32 v139, v142, v139
	v_div_scale_f32 v142, vcc, 1.0, v134, 1.0
	v_mul_f32_e32 v143, v142, v139
	v_fma_f32 v146, -v138, v143, v142
	v_fmac_f32_e32 v143, v146, v139
	v_fma_f32 v138, -v138, v143, v142
	v_div_fmas_f32 v138, v138, v139, v143
	v_div_fixup_f32 v134, v138, v134, 1.0
	v_pk_mul_f32 v[130:131], v[130:131], v[134:135]
	v_mov_b32_dpp v138, v60 row_shr:1 row_mask:0xf bank_mask:0xf bound_ctrl:1
	v_pk_mul_f32 v[134:135], v[50:51], v[130:131]
	v_mov_b32_dpp v130, v60 row_shr:2 row_mask:0xf bank_mask:0xf bound_ctrl:1
	v_mov_b32_dpp v131, v61 row_shr:2 row_mask:0xf bank_mask:0xf bound_ctrl:1
	v_cndmask_b32_e64 v130, v130, v132, s[16:17]
	v_cndmask_b32_e64 v131, v131, v133, s[16:17]
	v_mov_b32_dpp v139, v61 row_shr:1 row_mask:0xf bank_mask:0xf bound_ctrl:1
	v_cndmask_b32_e64 v131, v131, v153, s[18:19]
	v_cndmask_b32_e64 v130, v130, v152, s[18:19]
	v_cndmask_b32_e64 v133, v139, v153, s[16:17]
	v_cndmask_b32_e64 v132, v138, v152, s[16:17]
	v_pk_fma_f32 v[130:131], v[140:141], v[130:131], v[148:149]
	v_mov_b32_dpp v169, v168 quad_perm:[1,0,3,2] row_mask:0xf bank_mask:0xf bound_ctrl:1
	v_pk_fma_f32 v[130:131], v[144:145], v[132:133], v[130:131]
	v_mov_b32_dpp v175, v171 quad_perm:[1,0,3,2] row_mask:0xf bank_mask:0xf bound_ctrl:1
	v_pk_fma_f32 v[130:131], v[60:61], v[136:137], v[130:131]
	v_mov_b32_dpp v176, v9 row_shr:2 row_mask:0xf bank_mask:0xf bound_ctrl:1
	v_mul_f32_e32 v132, 0xbfb8aa3b, v130
	v_mul_f32_e32 v133, 0xbfb8aa3b, v131
	v_exp_f32_e32 v132, v132
	v_exp_f32_e32 v133, v133
	v_mov_b32_dpp v177, v174 quad_perm:[1,0,3,2] row_mask:0xf bank_mask:0xf bound_ctrl:1
	v_mov_b32_dpp v170, v8 row_shr:1 row_mask:0xf bank_mask:0xf bound_ctrl:1
	v_mov_b32_dpp v172, v9 row_shr:1 row_mask:0xf bank_mask:0xf bound_ctrl:1
	v_pk_add_f32 v[132:133], v[132:133], 1.0 op_sel_hi:[1,0]
	s_nop 0
	v_div_scale_f32 v136, s[2:3], v133, v133, 1.0
	v_rcp_f32_e32 v137, v136
	s_nop 0
	v_fma_f32 v138, -v136, v137, 1.0
	v_fmac_f32_e32 v137, v138, v137
	v_div_scale_f32 v138, vcc, 1.0, v133, 1.0
	v_mul_f32_e32 v139, v138, v137
	v_fma_f32 v140, -v136, v139, v138
	v_fmac_f32_e32 v139, v140, v137
	v_fma_f32 v136, -v136, v139, v138
	v_div_fmas_f32 v136, v136, v137, v139
	v_div_fixup_f32 v133, v136, v133, 1.0
	v_div_scale_f32 v136, s[2:3], v132, v132, 1.0
	v_rcp_f32_e32 v137, v136
	s_nop 0
	v_fma_f32 v138, -v136, v137, 1.0
	v_fmac_f32_e32 v137, v138, v137
	v_div_scale_f32 v138, vcc, 1.0, v132, 1.0
	v_mul_f32_e32 v139, v138, v137
	v_fma_f32 v140, -v136, v139, v138
	v_fmac_f32_e32 v139, v140, v137
	v_fma_f32 v136, -v136, v139, v138
	v_div_fmas_f32 v136, v136, v137, v139
	v_div_fixup_f32 v132, v136, v132, 1.0
	v_pk_mul_f32 v[130:131], v[130:131], v[132:133]
	v_cvt_pk_bf16_f32 v132, v134, v135
	v_pk_mul_f32 v[136:137], v[52:53], v[130:131]
	v_cvt_pk_bf16_f32 v130, v154, v155
	v_cvt_pk_bf16_f32 v131, v156, v157
	v_cvt_pk_bf16_f32 v133, v136, v137
	v_mad_i64_i32 v[134:135], s[2:3], v158, s40, v[190:191]
	global_load_dwordx4 v[146:149], v[198:199], off
	s_nop 0
	global_load_dwordx4 v[150:153], v[196:197], off
	s_nop 0
	global_load_dwordx4 v[154:157], v[194:195], off
	s_nop 0
	global_load_dwordx4 v[158:161], v[192:193], off
	s_nop 0
	global_store_dwordx4 v[134:135], v[130:133], off
	s_nop 3
	global_load_dwordx4 v[130:133], v[198:199], off offset:16
	s_nop 0
	global_load_dwordx4 v[138:141], v[196:197], off offset:16
	s_nop 0
	global_load_dwordx4 v[134:137], v[194:195], off offset:16
	s_nop 0
	global_load_dwordx4 v[142:145], v[192:193], off offset:16
	s_nop 0
	s_waitcnt vmcnt(5)
; DI float sigmoidf_(float x) { return 1.f / (1.f + __expf(-x)); }
; DI void up_epilogue(const PRef& p, int l, const f32x4 (&acc)[2][2][4][2], int brow, int bcol, int wr, int wc, int fr, int fq, float* exch) {
;     ...
;       for (int n = 0; n < 2; ++n) {
;         const int c = cw0 + n * 4;
;         const float4 w0 = *reinterpret_cast<const float4*>(cwp + c), w1 = *reinterpret_cast<const float4*>(cwp + DFF + c);
;         const float4 w2 = *reinterpret_cast<const float4*>(cwp + 2 * DFF + c), bs = *reinterpret_cast<const float4*>(cbp + c);
;         const float w0a[4] = {w0.x, w0.y, w0.z, w0.w}, w1a[4] = {w1.x, w1.y, w1.z, w1.w}, w2a[4] = {w2.x, w2.y, w2.z, w2.w}, bsa[4] = {bs.x, bs.y, bs.z, bs.w};
;         float p62a[4] = {0.f, 0.f, 0.f, 0.f}, p63a[4] = {0.f, 0.f, 0.f, 0.f};
;         if (m == 0 && sp > 0) {
;           const float4 p62 = *reinterpret_cast<const float4*>(exch + (((sp - 1) * 2 + 0) * 128 + tc0 + n * 4));
;           const float4 p63 = *reinterpret_cast<const float4*>(exch + (((sp - 1) * 2 + 1) * 128 + tc0 + n * 4));
;           p62a[0] = p62.x; p62a[1] = p62.y; p62a[2] = p62.z; p62a[3] = p62.w;
;           p63a[0] = p63.x; p63a[1] = p63.y; p63a[2] = p63.z; p63a[3] = p63.w;
;         }
; #pragma unroll
;         for (int j = 0; j < 4; ++j) {
;           const float a = acc[ai][0][m][n][j], g = acc[ai][1][m][n][j];
;           float pr1 = dppz<0x111>(a), pr2 = dppz<0x112>(a);
;           if (m == 0) {
;             if (fr == 0) { pr1 = p63a[j]; pr2 = p62a[j]; }
;             if (fr == 1) { pr2 = p63a[j]; }
;           } else {
;             const float am = acc[ai][0][m > 0 ? m - 1 : 0][n][j];
;             const float mir = dppz<0x140>(am);
;             const float swp = dppz<0xB1>(mir);
;             if (fr == 0) { pr1 = mir; }
;             if (fr < 2) { pr2 = swp; }
;           }
;           const float cv = bsa[j] + w0a[j] * pr2 + w1a[j] * pr1 + w2a[j] * a;
;           o[n * 4 + j] = cv * sigmoidf_(cv) * g;
	v_pk_fma_f32 v[146:147], v[146:147], v[162:163], v[158:159]
	s_nop 0
	v_pk_fma_f32 v[146:147], v[150:151], v[164:165], v[146:147]
	v_mov_b32_dpp v165, v166 quad_perm:[1,0,3,2] row_mask:0xf bank_mask:0xf bound_ctrl:1
	v_pk_fma_f32 v[146:147], v[46:47], v[154:155], v[146:147]
	v_mov_b32_dpp v164, v30 row_shr:1 row_mask:0xf bank_mask:0xf bound_ctrl:1
	v_mul_f32_e32 v150, 0xbfb8aa3b, v146
	v_mul_f32_e32 v151, 0xbfb8aa3b, v147
	v_exp_f32_e32 v150, v150
	v_exp_f32_e32 v151, v151
	v_cndmask_b32_e64 v164, v164, v166, s[16:17]
	v_pk_add_f32 v[150:151], v[150:151], 1.0 op_sel_hi:[1,0]
	s_nop 0
	v_div_scale_f32 v154, s[2:3], v151, v151, 1.0
	v_rcp_f32_e32 v155, v154
	s_nop 0
	v_fma_f32 v158, -v154, v155, 1.0
	v_fmac_f32_e32 v155, v158, v155
	v_div_scale_f32 v158, vcc, 1.0, v151, 1.0
	v_mul_f32_e32 v159, v158, v155
	v_fma_f32 v162, -v154, v159, v158
	v_fmac_f32_e32 v159, v162, v155
	v_fma_f32 v154, -v154, v159, v158
	v_div_fmas_f32 v154, v154, v155, v159
	v_div_fixup_f32 v151, v154, v151, 1.0
	v_div_scale_f32 v154, s[2:3], v150, v150, 1.0
	v_rcp_f32_e32 v155, v154
	s_nop 0
	v_fma_f32 v158, -v154, v155, 1.0
	v_fmac_f32_e32 v155, v158, v155
	v_div_scale_f32 v158, vcc, 1.0, v150, 1.0
	v_mul_f32_e32 v159, v158, v155
	v_fma_f32 v162, -v154, v159, v158
	v_fmac_f32_e32 v159, v162, v155
	v_fma_f32 v154, -v154, v159, v158
	v_div_fmas_f32 v154, v154, v155, v159
	v_div_fixup_f32 v150, v154, v150, 1.0
	v_mov_b32_dpp v158, v64 row_mirror row_mask:0xf bank_mask:0xf bound_ctrl:1
	v_mov_b32_dpp v162, v65 row_mirror row_mask:0xf bank_mask:0xf bound_ctrl:1
	v_pk_mul_f32 v[146:147], v[146:147], v[150:151]
	v_mov_b32_dpp v150, v48 row_shr:2 row_mask:0xf bank_mask:0xf bound_ctrl:1
	v_mov_b32_dpp v155, v158 quad_perm:[1,0,3,2] row_mask:0xf bank_mask:0xf bound_ctrl:1
	v_mov_b32_dpp v151, v49 row_shr:2 row_mask:0xf bank_mask:0xf bound_ctrl:1
	v_mov_b32_dpp v163, v162 quad_perm:[1,0,3,2] row_mask:0xf bank_mask:0xf bound_ctrl:1
	v_mov_b32_dpp v154, v48 row_shr:1 row_mask:0xf bank_mask:0xf bound_ctrl:1
	v_mov_b32_dpp v159, v49 row_shr:1 row_mask:0xf bank_mask:0xf bound_ctrl:1
	v_cndmask_b32_e64 v151, v151, v163, s[14:15]
	v_cndmask_b32_e64 v150, v150, v155, s[14:15]
	v_cndmask_b32_e64 v155, v159, v162, s[16:17]
	v_cndmask_b32_e64 v154, v154, v158, s[16:17]
	v_pk_fma_f32 v[148:149], v[148:149], v[150:151], v[160:161]
	v_pk_mul_f32 v[146:147], v[38:39], v[146:147]
	v_pk_fma_f32 v[148:149], v[152:153], v[154:155], v[148:149]
	v_mov_b32_dpp v162, v30 row_shr:2 row_mask:0xf bank_mask:0xf bound_ctrl:1
	v_pk_fma_f32 v[148:149], v[48:49], v[156:157], v[148:149]
	v_mov_b32_dpp v163, v31 row_shr:2 row_mask:0xf bank_mask:0xf bound_ctrl:1
	v_mul_f32_e32 v150, 0xbfb8aa3b, v148
	v_mul_f32_e32 v151, 0xbfb8aa3b, v149
	v_exp_f32_e32 v150, v150
	v_exp_f32_e32 v151, v151
	v_cndmask_b32_e64 v163, v163, v169, s[14:15]
	v_cndmask_b32_e64 v162, v162, v165, s[14:15]
	v_cndmask_b32_e64 v165, v167, v168, s[16:17]
	v_pk_add_f32 v[150:151], v[150:151], 1.0 op_sel_hi:[1,0]
	v_mov_b32_dpp v167, v29 row_mirror row_mask:0xf bank_mask:0xf bound_ctrl:1
	v_div_scale_f32 v152, s[2:3], v151, v151, 1.0
	v_rcp_f32_e32 v153, v152
	v_mov_b32_dpp v168, v11 row_shr:2 row_mask:0xf bank_mask:0xf bound_ctrl:1
	v_mov_b32_dpp v169, v167 quad_perm:[1,0,3,2] row_mask:0xf bank_mask:0xf bound_ctrl:1
	v_fma_f32 v154, -v152, v153, 1.0
	v_fmac_f32_e32 v153, v154, v153
	v_div_scale_f32 v154, vcc, 1.0, v151, 1.0
	v_mul_f32_e32 v155, v154, v153
	v_fma_f32 v156, -v152, v155, v154
	v_fmac_f32_e32 v155, v156, v153
	v_fma_f32 v152, -v152, v155, v154
	v_div_fmas_f32 v152, v152, v153, v155
	v_div_fixup_f32 v151, v152, v151, 1.0
	v_div_scale_f32 v152, s[2:3], v150, v150, 1.0
	v_rcp_f32_e32 v153, v152
	s_nop 0
	v_fma_f32 v154, -v152, v153, 1.0
	v_fmac_f32_e32 v153, v154, v153
	v_div_scale_f32 v154, vcc, 1.0, v150, 1.0
	v_mul_f32_e32 v155, v154, v153
	v_fma_f32 v156, -v152, v155, v154
	v_fmac_f32_e32 v155, v156, v153
	v_fma_f32 v152, -v152, v155, v154
	v_div_fmas_f32 v152, v152, v153, v155
	v_div_fixup_f32 v150, v152, v150, 1.0
	v_mov_b32_dpp v154, v58 row_mirror row_mask:0xf bank_mask:0xf bound_ctrl:1
	v_mov_b32_dpp v156, v59 row_mirror row_mask:0xf bank_mask:0xf bound_ctrl:1
	v_pk_mul_f32 v[148:149], v[148:149], v[150:151]
	v_mov_b32_dpp v150, v42 row_shr:2 row_mask:0xf bank_mask:0xf bound_ctrl:1
	v_mov_b32_dpp v153, v154 quad_perm:[1,0,3,2] row_mask:0xf bank_mask:0xf bound_ctrl:1
	v_mov_b32_dpp v151, v43 row_shr:2 row_mask:0xf bank_mask:0xf bound_ctrl:1
	v_mov_b32_dpp v157, v156 quad_perm:[1,0,3,2] row_mask:0xf bank_mask:0xf bound_ctrl:1
	v_mov_b32_dpp v152, v42 row_shr:1 row_mask:0xf bank_mask:0xf bound_ctrl:1
	v_mov_b32_dpp v155, v43 row_shr:1 row_mask:0xf bank_mask:0xf bound_ctrl:1
	v_cndmask_b32_e64 v151, v151, v157, s[14:15]
	v_cndmask_b32_e64 v150, v150, v153, s[14:15]
	v_cndmask_b32_e64 v153, v155, v156, s[16:17]
	v_cndmask_b32_e64 v152, v152, v154, s[16:17]
	s_waitcnt vmcnt(0)
; DI unsigned pack2(float a, float b) { f32v2 v = {a, b}; return __builtin_bit_cast(unsigned, __builtin_convertvector(v, bf16v2)); }
; DI float sigmoidf_(float x) { return 1.f / (1.f + __expf(-x)); }
; DI void up_epilogue(const PRef& p, int l, const f32x4 (&acc)[2][2][4][2], int brow, int bcol, int wr, int wc, int fr, int fq, float* exch) {
;     ...
;       for (int n = 0; n < 2; ++n) {
;         const int c = cw0 + n * 4;
;         const float4 w0 = *reinterpret_cast<const float4*>(cwp + c), w1 = *reinterpret_cast<const float4*>(cwp + DFF + c);
;         const float4 w2 = *reinterpret_cast<const float4*>(cwp + 2 * DFF + c), bs = *reinterpret_cast<const float4*>(cbp + c);
;         const float w0a[4] = {w0.x, w0.y, w0.z, w0.w}, w1a[4] = {w1.x, w1.y, w1.z, w1.w}, w2a[4] = {w2.x, w2.y, w2.z, w2.w}, bsa[4] = {bs.x, bs.y, bs.z, bs.w};
;         float p62a[4] = {0.f, 0.f, 0.f, 0.f}, p63a[4] = {0.f, 0.f, 0.f, 0.f};
;         if (m == 0 && sp > 0) {
;           const float4 p62 = *reinterpret_cast<const float4*>(exch + (((sp - 1) * 2 + 0) * 128 + tc0 + n * 4));
;           const float4 p63 = *reinterpret_cast<const float4*>(exch + (((sp - 1) * 2 + 1) * 128 + tc0 + n * 4));
;           p62a[0] = p62.x; p62a[1] = p62.y; p62a[2] = p62.z; p62a[3] = p62.w;
;           p63a[0] = p63.x; p63a[1] = p63.y; p63a[2] = p63.z; p63a[3] = p63.w;
;         }
; #pragma unroll
;         for (int j = 0; j < 4; ++j) {
;           const float a = acc[ai][0][m][n][j], g = acc[ai][1][m][n][j];
;           float pr1 = dppz<0x111>(a), pr2 = dppz<0x112>(a);
;           if (m == 0) {
;             if (fr == 0) { pr1 = p63a[j]; pr2 = p62a[j]; }
;             if (fr == 1) { pr2 = p63a[j]; }
;           } else {
;             const float am = acc[ai][0][m > 0 ? m - 1 : 0][n][j];
;             const float mir = dppz<0x140>(am);
;             const float swp = dppz<0xB1>(mir);
;             if (fr == 0) { pr1 = mir; }
;             if (fr < 2) { pr2 = swp; }
;           }
;           const float cv = bsa[j] + w0a[j] * pr2 + w1a[j] * pr1 + w2a[j] * a;
;           o[n * 4 + j] = cv * sigmoidf_(cv) * g;
;         }
;       }
;       uint4 ov; ov.x = pack2(o[0], o[1]); ov.y = pack2(o[2], o[3]); ov.z = pack2(o[4], o[5]); ov.w = pack2(o[6], o[7]);
;       *reinterpret_cast<uint4*>(hmid + (size_t)(brow + ai * HALF + wr * 64 + m * 16 + fr) * DFF + cw0) = ov;
	v_pk_fma_f32 v[130:131], v[130:131], v[150:151], v[142:143]
	v_pk_mul_f32 v[148:149], v[40:41], v[148:149]
	v_pk_fma_f32 v[130:131], v[138:139], v[152:153], v[130:131]
	s_nop 0
	v_pk_fma_f32 v[130:131], v[42:43], v[134:135], v[130:131]
	s_nop 0
	v_mul_f32_e32 v134, 0xbfb8aa3b, v130
	v_mul_f32_e32 v135, 0xbfb8aa3b, v131
	v_exp_f32_e32 v134, v134
	v_exp_f32_e32 v135, v135
	s_nop 0
	v_pk_add_f32 v[134:135], v[134:135], 1.0 op_sel_hi:[1,0]
	s_nop 0
	v_div_scale_f32 v138, s[2:3], v135, v135, 1.0
	v_rcp_f32_e32 v139, v138
	s_nop 0
	v_fma_f32 v142, -v138, v139, 1.0
	v_fmac_f32_e32 v139, v142, v139
	v_div_scale_f32 v142, vcc, 1.0, v135, 1.0
	v_mul_f32_e32 v143, v142, v139
	v_fma_f32 v150, -v138, v143, v142
	v_fmac_f32_e32 v143, v150, v139
	v_fma_f32 v138, -v138, v143, v142
	v_div_fmas_f32 v138, v138, v139, v143
	v_div_fixup_f32 v135, v138, v135, 1.0
	v_div_scale_f32 v138, s[2:3], v134, v134, 1.0
	v_rcp_f32_e32 v139, v138
	s_nop 0
	v_fma_f32 v142, -v138, v139, 1.0
	v_fmac_f32_e32 v139, v142, v139
	v_div_scale_f32 v142, vcc, 1.0, v134, 1.0
	v_mul_f32_e32 v143, v142, v139
	v_fma_f32 v150, -v138, v143, v142
	v_fmac_f32_e32 v143, v150, v139
	v_fma_f32 v138, -v138, v143, v142
	v_div_fmas_f32 v138, v138, v139, v143
	v_div_fixup_f32 v134, v138, v134, 1.0
	v_pk_mul_f32 v[130:131], v[130:131], v[134:135]
	v_mov_b32_dpp v142, v60 row_mirror row_mask:0xf bank_mask:0xf bound_ctrl:1
	v_mov_b32_dpp v150, v61 row_mirror row_mask:0xf bank_mask:0xf bound_ctrl:1
	v_pk_mul_f32 v[134:135], v[34:35], v[130:131]
	v_mov_b32_dpp v130, v44 row_shr:2 row_mask:0xf bank_mask:0xf bound_ctrl:1
	v_mov_b32_dpp v139, v142 quad_perm:[1,0,3,2] row_mask:0xf bank_mask:0xf bound_ctrl:1
	v_mov_b32_dpp v131, v45 row_shr:2 row_mask:0xf bank_mask:0xf bound_ctrl:1
	v_mov_b32_dpp v151, v150 quad_perm:[1,0,3,2] row_mask:0xf bank_mask:0xf bound_ctrl:1
	v_mov_b32_dpp v138, v44 row_shr:1 row_mask:0xf bank_mask:0xf bound_ctrl:1
	v_mov_b32_dpp v143, v45 row_shr:1 row_mask:0xf bank_mask:0xf bound_ctrl:1
	v_cndmask_b32_e64 v131, v131, v151, s[14:15]
	v_cndmask_b32_e64 v130, v130, v139, s[14:15]
	v_cndmask_b32_e64 v139, v143, v150, s[16:17]
	v_cndmask_b32_e64 v138, v138, v142, s[16:17]
	v_pk_fma_f32 v[130:131], v[132:133], v[130:131], v[144:145]
	s_nop 0
	v_pk_fma_f32 v[130:131], v[140:141], v[138:139], v[130:131]
	s_nop 0
	v_pk_fma_f32 v[130:131], v[44:45], v[136:137], v[130:131]
	s_nop 0
	v_mul_f32_e32 v132, 0xbfb8aa3b, v130
	v_mul_f32_e32 v133, 0xbfb8aa3b, v131
	v_exp_f32_e32 v132, v132
	v_exp_f32_e32 v133, v133
	s_nop 0
	v_pk_add_f32 v[132:133], v[132:133], 1.0 op_sel_hi:[1,0]
	s_nop 0
	v_div_scale_f32 v136, s[2:3], v133, v133, 1.0
	v_rcp_f32_e32 v137, v136
	s_nop 0
	v_fma_f32 v138, -v136, v137, 1.0
	v_fmac_f32_e32 v137, v138, v137
	v_div_scale_f32 v138, vcc, 1.0, v133, 1.0
	v_mul_f32_e32 v139, v138, v137
	v_fma_f32 v140, -v136, v139, v138
	v_fmac_f32_e32 v139, v140, v137
	v_fma_f32 v136, -v136, v139, v138
	v_div_fmas_f32 v136, v136, v137, v139
	v_div_fixup_f32 v133, v136, v133, 1.0
	v_div_scale_f32 v136, s[2:3], v132, v132, 1.0
	v_rcp_f32_e32 v137, v136
	s_nop 0
	v_fma_f32 v138, -v136, v137, 1.0
	v_fmac_f32_e32 v137, v138, v137
	v_div_scale_f32 v138, vcc, 1.0, v132, 1.0
	v_mul_f32_e32 v139, v138, v137
	v_fma_f32 v140, -v136, v139, v138
	v_fmac_f32_e32 v139, v140, v137
	v_fma_f32 v136, -v136, v139, v138
	v_div_fmas_f32 v136, v136, v137, v139
	v_div_fixup_f32 v132, v136, v132, 1.0
	v_pk_mul_f32 v[130:131], v[130:131], v[132:133]
	v_cvt_pk_bf16_f32 v132, v134, v135
	v_pk_mul_f32 v[136:137], v[36:37], v[130:131]
	v_add_u32_e32 v134, 0x90, v16
	v_cvt_pk_bf16_f32 v130, v146, v147
	v_cvt_pk_bf16_f32 v131, v148, v149
	v_cvt_pk_bf16_f32 v133, v136, v137
	v_mad_i64_i32 v[134:135], s[2:3], v134, s40, v[190:191]
	global_load_dwordx4 v[146:149], v[198:199], off
	s_nop 0
	global_load_dwordx4 v[150:153], v[196:197], off
	s_nop 0
	global_load_dwordx4 v[154:157], v[194:195], off
	s_nop 0
	global_load_dwordx4 v[158:161], v[192:193], off
	s_nop 0
	global_store_dwordx4 v[134:135], v[130:133], off
	s_nop 3
	global_load_dwordx4 v[130:133], v[198:199], off offset:16
	s_nop 0
	global_load_dwordx4 v[138:141], v[196:197], off offset:16
	s_nop 0
	global_load_dwordx4 v[134:137], v[194:195], off offset:16
	s_nop 0
	global_load_dwordx4 v[142:145], v[192:193], off offset:16
	s_nop 0
	s_waitcnt vmcnt(5)
; DI float sigmoidf_(float x) { return 1.f / (1.f + __expf(-x)); }
; DI void up_epilogue(const PRef& p, int l, const f32x4 (&acc)[2][2][4][2], int brow, int bcol, int wr, int wc, int fr, int fq, float* exch) {
;     ...
;       for (int n = 0; n < 2; ++n) {
;         const int c = cw0 + n * 4;
;         const float4 w0 = *reinterpret_cast<const float4*>(cwp + c), w1 = *reinterpret_cast<const float4*>(cwp + DFF + c);
;         const float4 w2 = *reinterpret_cast<const float4*>(cwp + 2 * DFF + c), bs = *reinterpret_cast<const float4*>(cbp + c);
;         const float w0a[4] = {w0.x, w0.y, w0.z, w0.w}, w1a[4] = {w1.x, w1.y, w1.z, w1.w}, w2a[4] = {w2.x, w2.y, w2.z, w2.w}, bsa[4] = {bs.x, bs.y, bs.z, bs.w};
;         float p62a[4] = {0.f, 0.f, 0.f, 0.f}, p63a[4] = {0.f, 0.f, 0.f, 0.f};
;         if (m == 0 && sp > 0) {
;           const float4 p62 = *reinterpret_cast<const float4*>(exch + (((sp - 1) * 2 + 0) * 128 + tc0 + n * 4));
;           const float4 p63 = *reinterpret_cast<const float4*>(exch + (((sp - 1) * 2 + 1) * 128 + tc0 + n * 4));
;           p62a[0] = p62.x; p62a[1] = p62.y; p62a[2] = p62.z; p62a[3] = p62.w;
;           p63a[0] = p63.x; p63a[1] = p63.y; p63a[2] = p63.z; p63a[3] = p63.w;
;         }
; #pragma unroll
;         for (int j = 0; j < 4; ++j) {
;           const float a = acc[ai][0][m][n][j], g = acc[ai][1][m][n][j];
;           float pr1 = dppz<0x111>(a), pr2 = dppz<0x112>(a);
;           if (m == 0) {
;             if (fr == 0) { pr1 = p63a[j]; pr2 = p62a[j]; }
;             if (fr == 1) { pr2 = p63a[j]; }
;           } else {
;             const float am = acc[ai][0][m > 0 ? m - 1 : 0][n][j];
;             const float mir = dppz<0x140>(am);
;             const float swp = dppz<0xB1>(mir);
;             if (fr == 0) { pr1 = mir; }
;             if (fr < 2) { pr2 = swp; }
;           }
;           const float cv = bsa[j] + w0a[j] * pr2 + w1a[j] * pr1 + w2a[j] * a;
;           o[n * 4 + j] = cv * sigmoidf_(cv) * g;
	v_pk_fma_f32 v[146:147], v[146:147], v[162:163], v[158:159]
	s_nop 0
	v_pk_fma_f32 v[146:147], v[150:151], v[164:165], v[146:147]
	v_mov_b32_dpp v164, v10 row_shr:2 row_mask:0xf bank_mask:0xf bound_ctrl:1
	v_pk_fma_f32 v[146:147], v[30:31], v[154:155], v[146:147]
	v_mov_b32_dpp v165, v11 row_shr:1 row_mask:0xf bank_mask:0xf bound_ctrl:1
	v_mul_f32_e32 v150, 0xbfb8aa3b, v146
	v_mul_f32_e32 v151, 0xbfb8aa3b, v147
	v_exp_f32_e32 v150, v150
	v_exp_f32_e32 v151, v151
	s_nop 0
	v_pk_add_f32 v[150:151], v[150:151], 1.0 op_sel_hi:[1,0]
	s_nop 0
	v_div_scale_f32 v154, s[2:3], v151, v151, 1.0
	v_rcp_f32_e32 v155, v154
	s_nop 0
	v_fma_f32 v158, -v154, v155, 1.0
	v_fmac_f32_e32 v155, v158, v155
	v_div_scale_f32 v158, vcc, 1.0, v151, 1.0
	v_mul_f32_e32 v159, v158, v155
	v_fma_f32 v162, -v154, v159, v158
	v_fmac_f32_e32 v159, v162, v155
	v_fma_f32 v154, -v154, v159, v158
	v_div_fmas_f32 v154, v154, v155, v159
	v_div_fixup_f32 v151, v154, v151, 1.0
	v_div_scale_f32 v154, s[2:3], v150, v150, 1.0
	v_rcp_f32_e32 v155, v154
	s_nop 0
	v_fma_f32 v158, -v154, v155, 1.0
	v_fmac_f32_e32 v155, v158, v155
	v_div_scale_f32 v158, vcc, 1.0, v150, 1.0
	v_mul_f32_e32 v159, v158, v155
	v_fma_f32 v162, -v154, v159, v158
	v_fmac_f32_e32 v159, v162, v155
	v_fma_f32 v154, -v154, v159, v158
	v_div_fmas_f32 v154, v154, v155, v159
	v_div_fixup_f32 v150, v154, v150, 1.0
	v_mov_b32_dpp v158, v48 row_mirror row_mask:0xf bank_mask:0xf bound_ctrl:1
	v_mov_b32_dpp v162, v49 row_mirror row_mask:0xf bank_mask:0xf bound_ctrl:1
	v_pk_mul_f32 v[146:147], v[146:147], v[150:151]
	v_mov_b32_dpp v150, v32 row_shr:2 row_mask:0xf bank_mask:0xf bound_ctrl:1
	v_mov_b32_dpp v155, v158 quad_perm:[1,0,3,2] row_mask:0xf bank_mask:0xf bound_ctrl:1
	v_mov_b32_dpp v151, v33 row_shr:2 row_mask:0xf bank_mask:0xf bound_ctrl:1
	v_mov_b32_dpp v163, v162 quad_perm:[1,0,3,2] row_mask:0xf bank_mask:0xf bound_ctrl:1
	v_mov_b32_dpp v154, v32 row_shr:1 row_mask:0xf bank_mask:0xf bound_ctrl:1
	v_mov_b32_dpp v159, v33 row_shr:1 row_mask:0xf bank_mask:0xf bound_ctrl:1
	v_cndmask_b32_e64 v151, v151, v163, s[14:15]
	v_cndmask_b32_e64 v150, v150, v155, s[14:15]
	v_cndmask_b32_e64 v155, v159, v162, s[16:17]
	v_cndmask_b32_e64 v154, v154, v158, s[16:17]
	v_pk_fma_f32 v[148:149], v[148:149], v[150:151], v[160:161]
	v_pk_mul_f32 v[146:147], v[22:23], v[146:147]
	v_pk_fma_f32 v[148:149], v[152:153], v[154:155], v[148:149]
	v_mov_b32_dpp v163, v28 row_mirror row_mask:0xf bank_mask:0xf bound_ctrl:1
	v_pk_fma_f32 v[148:149], v[32:33], v[156:157], v[148:149]
	v_mov_b32_dpp v162, v10 row_shr:1 row_mask:0xf bank_mask:0xf bound_ctrl:1
	v_mul_f32_e32 v150, 0xbfb8aa3b, v148
	v_mul_f32_e32 v151, 0xbfb8aa3b, v149
	v_exp_f32_e32 v150, v150
	v_exp_f32_e32 v151, v151
	v_mov_b32_dpp v166, v163 quad_perm:[1,0,3,2] row_mask:0xf bank_mask:0xf bound_ctrl:1
	v_pk_add_f32 v[150:151], v[150:151], 1.0 op_sel_hi:[1,0]
	s_nop 0
	v_div_scale_f32 v152, s[2:3], v151, v151, 1.0
	v_rcp_f32_e32 v153, v152
	s_nop 0
	v_fma_f32 v154, -v152, v153, 1.0
	v_fmac_f32_e32 v153, v154, v153
	v_div_scale_f32 v154, vcc, 1.0, v151, 1.0
	v_mul_f32_e32 v155, v154, v153
	v_fma_f32 v156, -v152, v155, v154
	v_fmac_f32_e32 v155, v156, v153
	v_fma_f32 v152, -v152, v155, v154
	v_div_fmas_f32 v152, v152, v153, v155
	v_div_fixup_f32 v151, v152, v151, 1.0
	v_div_scale_f32 v152, s[2:3], v150, v150, 1.0
	v_rcp_f32_e32 v153, v152
	s_nop 0
	v_fma_f32 v154, -v152, v153, 1.0
	v_fmac_f32_e32 v153, v154, v153
	v_div_scale_f32 v154, vcc, 1.0, v150, 1.0
	v_mul_f32_e32 v155, v154, v153
	v_fma_f32 v156, -v152, v155, v154
	v_fmac_f32_e32 v155, v156, v153
	v_fma_f32 v152, -v152, v155, v154
	v_div_fmas_f32 v152, v152, v153, v155
	v_div_fixup_f32 v150, v152, v150, 1.0
	v_mov_b32_dpp v154, v42 row_mirror row_mask:0xf bank_mask:0xf bound_ctrl:1
	v_mov_b32_dpp v156, v43 row_mirror row_mask:0xf bank_mask:0xf bound_ctrl:1
	v_pk_mul_f32 v[148:149], v[148:149], v[150:151]
	v_mov_b32_dpp v150, v26 row_shr:2 row_mask:0xf bank_mask:0xf bound_ctrl:1
	v_mov_b32_dpp v153, v154 quad_perm:[1,0,3,2] row_mask:0xf bank_mask:0xf bound_ctrl:1
	v_mov_b32_dpp v151, v27 row_shr:2 row_mask:0xf bank_mask:0xf bound_ctrl:1
	v_mov_b32_dpp v157, v156 quad_perm:[1,0,3,2] row_mask:0xf bank_mask:0xf bound_ctrl:1
	v_mov_b32_dpp v152, v26 row_shr:1 row_mask:0xf bank_mask:0xf bound_ctrl:1
	v_mov_b32_dpp v155, v27 row_shr:1 row_mask:0xf bank_mask:0xf bound_ctrl:1
	v_cndmask_b32_e64 v151, v151, v157, s[14:15]
	v_cndmask_b32_e64 v150, v150, v153, s[14:15]
	v_cndmask_b32_e64 v153, v155, v156, s[16:17]
	v_cndmask_b32_e64 v152, v152, v154, s[16:17]
	s_waitcnt vmcnt(0)
; DI unsigned pack2(float a, float b) { f32v2 v = {a, b}; return __builtin_bit_cast(unsigned, __builtin_convertvector(v, bf16v2)); }
; DI float sigmoidf_(float x) { return 1.f / (1.f + __expf(-x)); }
; DI void up_epilogue(const PRef& p, int l, const f32x4 (&acc)[2][2][4][2], int brow, int bcol, int wr, int wc, int fr, int fq, float* exch) {
;     ...
;       for (int n = 0; n < 2; ++n) {
;         const int c = cw0 + n * 4;
;         const float4 w0 = *reinterpret_cast<const float4*>(cwp + c), w1 = *reinterpret_cast<const float4*>(cwp + DFF + c);
;         const float4 w2 = *reinterpret_cast<const float4*>(cwp + 2 * DFF + c), bs = *reinterpret_cast<const float4*>(cbp + c);
;         const float w0a[4] = {w0.x, w0.y, w0.z, w0.w}, w1a[4] = {w1.x, w1.y, w1.z, w1.w}, w2a[4] = {w2.x, w2.y, w2.z, w2.w}, bsa[4] = {bs.x, bs.y, bs.z, bs.w};
;         float p62a[4] = {0.f, 0.f, 0.f, 0.f}, p63a[4] = {0.f, 0.f, 0.f, 0.f};
;         if (m == 0 && sp > 0) {
;           const float4 p62 = *reinterpret_cast<const float4*>(exch + (((sp - 1) * 2 + 0) * 128 + tc0 + n * 4));
;           const float4 p63 = *reinterpret_cast<const float4*>(exch + (((sp - 1) * 2 + 1) * 128 + tc0 + n * 4));
;           p62a[0] = p62.x; p62a[1] = p62.y; p62a[2] = p62.z; p62a[3] = p62.w;
;           p63a[0] = p63.x; p63a[1] = p63.y; p63a[2] = p63.z; p63a[3] = p63.w;
;         }
; #pragma unroll
;         for (int j = 0; j < 4; ++j) {
;           const float a = acc[ai][0][m][n][j], g = acc[ai][1][m][n][j];
;           float pr1 = dppz<0x111>(a), pr2 = dppz<0x112>(a);
;           if (m == 0) {
;             if (fr == 0) { pr1 = p63a[j]; pr2 = p62a[j]; }
;             if (fr == 1) { pr2 = p63a[j]; }
;           } else {
;             const float am = acc[ai][0][m > 0 ? m - 1 : 0][n][j];
;             const float mir = dppz<0x140>(am);
;             const float swp = dppz<0xB1>(mir);
;             if (fr == 0) { pr1 = mir; }
;             if (fr < 2) { pr2 = swp; }
;           }
;           const float cv = bsa[j] + w0a[j] * pr2 + w1a[j] * pr1 + w2a[j] * a;
;           o[n * 4 + j] = cv * sigmoidf_(cv) * g;
;         }
;       }
;       uint4 ov; ov.x = pack2(o[0], o[1]); ov.y = pack2(o[2], o[3]); ov.z = pack2(o[4], o[5]); ov.w = pack2(o[6], o[7]);
;       *reinterpret_cast<uint4*>(hmid + (size_t)(brow + ai * HALF + wr * 64 + m * 16 + fr) * DFF + cw0) = ov;
	v_pk_fma_f32 v[130:131], v[130:131], v[150:151], v[142:143]
	v_pk_mul_f32 v[148:149], v[24:25], v[148:149]
	v_pk_fma_f32 v[130:131], v[138:139], v[152:153], v[130:131]
	s_nop 0
	v_pk_fma_f32 v[130:131], v[26:27], v[134:135], v[130:131]
	s_nop 0
	v_mul_f32_e32 v134, 0xbfb8aa3b, v130
	v_mul_f32_e32 v135, 0xbfb8aa3b, v131
	v_exp_f32_e32 v134, v134
	v_exp_f32_e32 v135, v135
	s_nop 0
	v_pk_add_f32 v[134:135], v[134:135], 1.0 op_sel_hi:[1,0]
	s_nop 0
	v_div_scale_f32 v138, s[2:3], v135, v135, 1.0
	v_rcp_f32_e32 v139, v138
	s_nop 0
	v_fma_f32 v142, -v138, v139, 1.0
	v_fmac_f32_e32 v139, v142, v139
	v_div_scale_f32 v142, vcc, 1.0, v135, 1.0
	v_mul_f32_e32 v143, v142, v139
	v_fma_f32 v150, -v138, v143, v142
	v_fmac_f32_e32 v143, v150, v139
	v_fma_f32 v138, -v138, v143, v142
	v_div_fmas_f32 v138, v138, v139, v143
	v_div_fixup_f32 v135, v138, v135, 1.0
	v_div_scale_f32 v138, s[2:3], v134, v134, 1.0
	v_rcp_f32_e32 v139, v138
	s_nop 0
	v_fma_f32 v142, -v138, v139, 1.0
	v_fmac_f32_e32 v139, v142, v139
	v_div_scale_f32 v142, vcc, 1.0, v134, 1.0
	v_mul_f32_e32 v143, v142, v139
	v_fma_f32 v150, -v138, v143, v142
	v_fmac_f32_e32 v143, v150, v139
	v_fma_f32 v138, -v138, v143, v142
	v_div_fmas_f32 v138, v138, v139, v143
	v_div_fixup_f32 v134, v138, v134, 1.0
	v_pk_mul_f32 v[130:131], v[130:131], v[134:135]
	v_mov_b32_dpp v142, v44 row_mirror row_mask:0xf bank_mask:0xf bound_ctrl:1
	v_mov_b32_dpp v150, v45 row_mirror row_mask:0xf bank_mask:0xf bound_ctrl:1
	v_pk_mul_f32 v[134:135], v[18:19], v[130:131]
	v_mov_b32_dpp v130, v28 row_shr:2 row_mask:0xf bank_mask:0xf bound_ctrl:1
	v_mov_b32_dpp v139, v142 quad_perm:[1,0,3,2] row_mask:0xf bank_mask:0xf bound_ctrl:1
	v_mov_b32_dpp v131, v29 row_shr:2 row_mask:0xf bank_mask:0xf bound_ctrl:1
	v_mov_b32_dpp v151, v150 quad_perm:[1,0,3,2] row_mask:0xf bank_mask:0xf bound_ctrl:1
	v_mov_b32_dpp v138, v28 row_shr:1 row_mask:0xf bank_mask:0xf bound_ctrl:1
	v_mov_b32_dpp v143, v29 row_shr:1 row_mask:0xf bank_mask:0xf bound_ctrl:1
	v_cndmask_b32_e64 v131, v131, v151, s[14:15]
	v_cndmask_b32_e64 v130, v130, v139, s[14:15]
	v_cndmask_b32_e64 v139, v143, v150, s[16:17]
	v_cndmask_b32_e64 v138, v138, v142, s[16:17]
	v_pk_fma_f32 v[130:131], v[132:133], v[130:131], v[144:145]
	s_nop 0
	v_pk_fma_f32 v[130:131], v[140:141], v[138:139], v[130:131]
	s_nop 0
	v_pk_fma_f32 v[130:131], v[28:29], v[136:137], v[130:131]
	s_nop 0
	v_mul_f32_e32 v132, 0xbfb8aa3b, v130
	v_mul_f32_e32 v133, 0xbfb8aa3b, v131
	v_exp_f32_e32 v132, v132
	v_exp_f32_e32 v133, v133
	s_nop 0
	v_pk_add_f32 v[132:133], v[132:133], 1.0 op_sel_hi:[1,0]
	s_nop 0
	v_div_scale_f32 v136, s[2:3], v133, v133, 1.0
	v_rcp_f32_e32 v137, v136
	s_nop 0
	v_fma_f32 v138, -v136, v137, 1.0
	v_fmac_f32_e32 v137, v138, v137
	v_div_scale_f32 v138, vcc, 1.0, v133, 1.0
	v_mul_f32_e32 v139, v138, v137
	v_fma_f32 v140, -v136, v139, v138
	v_fmac_f32_e32 v139, v140, v137
	v_fma_f32 v136, -v136, v139, v138
	v_div_fmas_f32 v136, v136, v137, v139
	v_div_fixup_f32 v133, v136, v133, 1.0
	v_div_scale_f32 v136, s[2:3], v132, v132, 1.0
	v_rcp_f32_e32 v137, v136
	s_nop 0
	v_fma_f32 v138, -v136, v137, 1.0
	v_fmac_f32_e32 v137, v138, v137
	v_div_scale_f32 v138, vcc, 1.0, v132, 1.0
	v_mul_f32_e32 v139, v138, v137
	v_fma_f32 v140, -v136, v139, v138
	v_fmac_f32_e32 v139, v140, v137
	v_fma_f32 v136, -v136, v139, v138
	v_div_fmas_f32 v136, v136, v137, v139
	v_div_fixup_f32 v132, v136, v132, 1.0
	v_pk_mul_f32 v[130:131], v[130:131], v[132:133]
	v_cvt_pk_bf16_f32 v132, v134, v135
	v_pk_mul_f32 v[136:137], v[20:21], v[130:131]
	v_add_u32_e32 v134, 0xa0, v16
	v_cvt_pk_bf16_f32 v130, v146, v147
	v_cvt_pk_bf16_f32 v131, v148, v149
	v_cvt_pk_bf16_f32 v133, v136, v137
	v_mad_i64_i32 v[134:135], s[2:3], v134, s40, v[190:191]
	global_load_dwordx4 v[154:157], v[198:199], off
	s_nop 0
	global_load_dwordx4 v[146:149], v[196:197], off
	s_nop 0
	global_load_dwordx4 v[150:153], v[194:195], off
	s_nop 0
	global_load_dwordx4 v[158:161], v[192:193], off
	s_nop 0
	global_store_dwordx4 v[134:135], v[130:133], off
	s_nop 3
	global_load_dwordx4 v[130:133], v[198:199], off offset:16
	s_nop 0
	global_load_dwordx4 v[138:141], v[196:197], off offset:16
	s_nop 0
	global_load_dwordx4 v[134:137], v[194:195], off offset:16
	s_nop 0
	global_load_dwordx4 v[142:145], v[192:193], off offset:16
	s_nop 0
	v_cndmask_b32_e64 v193, v215, v217, s[14:15]
	v_cndmask_b32_e64 v192, v201, v203, s[14:15]
	v_add_u32_e32 v16, 0xb0, v16
	s_waitcnt vmcnt(5)
; DI unsigned pack2(float a, float b) { f32v2 v = {a, b}; return __builtin_bit_cast(unsigned, __builtin_convertvector(v, bf16v2)); }
; DI float sigmoidf_(float x) { return 1.f / (1.f + __expf(-x)); }
; DI void up_epilogue(const PRef& p, int l, const f32x4 (&acc)[2][2][4][2], int brow, int bcol, int wr, int wc, int fr, int fq, float* exch) {
;     ...
;       for (int n = 0; n < 2; ++n) {
;         const int c = cw0 + n * 4;
;         const float4 w0 = *reinterpret_cast<const float4*>(cwp + c), w1 = *reinterpret_cast<const float4*>(cwp + DFF + c);
;         const float4 w2 = *reinterpret_cast<const float4*>(cwp + 2 * DFF + c), bs = *reinterpret_cast<const float4*>(cbp + c);
;         const float w0a[4] = {w0.x, w0.y, w0.z, w0.w}, w1a[4] = {w1.x, w1.y, w1.z, w1.w}, w2a[4] = {w2.x, w2.y, w2.z, w2.w}, bsa[4] = {bs.x, bs.y, bs.z, bs.w};
;         float p62a[4] = {0.f, 0.f, 0.f, 0.f}, p63a[4] = {0.f, 0.f, 0.f, 0.f};
;         if (m == 0 && sp > 0) {
;           const float4 p62 = *reinterpret_cast<const float4*>(exch + (((sp - 1) * 2 + 0) * 128 + tc0 + n * 4));
;           const float4 p63 = *reinterpret_cast<const float4*>(exch + (((sp - 1) * 2 + 1) * 128 + tc0 + n * 4));
;           p62a[0] = p62.x; p62a[1] = p62.y; p62a[2] = p62.z; p62a[3] = p62.w;
;           p63a[0] = p63.x; p63a[1] = p63.y; p63a[2] = p63.z; p63a[3] = p63.w;
;         }
; #pragma unroll
;         for (int j = 0; j < 4; ++j) {
;           const float a = acc[ai][0][m][n][j], g = acc[ai][1][m][n][j];
;           float pr1 = dppz<0x111>(a), pr2 = dppz<0x112>(a);
;           if (m == 0) {
;             if (fr == 0) { pr1 = p63a[j]; pr2 = p62a[j]; }
;             if (fr == 1) { pr2 = p63a[j]; }
;           } else {
;             const float am = acc[ai][0][m > 0 ? m - 1 : 0][n][j];
;             const float mir = dppz<0x140>(am);
;             const float swp = dppz<0xB1>(mir);
;             if (fr == 0) { pr1 = mir; }
;             if (fr < 2) { pr2 = swp; }
;           }
;           const float cv = bsa[j] + w0a[j] * pr2 + w1a[j] * pr1 + w2a[j] * a;
;           o[n * 4 + j] = cv * sigmoidf_(cv) * g;
;         }
;       }
;       uint4 ov; ov.x = pack2(o[0], o[1]); ov.y = pack2(o[2], o[3]); ov.z = pack2(o[4], o[5]); ov.w = pack2(o[6], o[7]);
;       *reinterpret_cast<uint4*>(hmid + (size_t)(brow + ai * HALF + wr * 64 + m * 16 + fr) * DFF + cw0) = ov;
;     }
;   }
;   __syncthreads();
	v_pk_fma_f32 v[154:155], v[154:155], v[192:193], v[158:159]
	v_cndmask_b32_e64 v159, v214, v216, s[16:17]
	v_cndmask_b32_e64 v158, v200, v202, s[16:17]
	v_pk_fma_f32 v[146:147], v[146:147], v[158:159], v[154:155]
	s_nop 0
	v_pk_fma_f32 v[146:147], v[12:13], v[150:151], v[146:147]
	s_nop 0
	v_mul_f32_e32 v150, 0xbfb8aa3b, v146
	v_mul_f32_e32 v151, 0xbfb8aa3b, v147
	v_exp_f32_e32 v150, v150
	v_exp_f32_e32 v151, v151
	s_nop 0
	v_pk_add_f32 v[150:151], v[150:151], 1.0 op_sel_hi:[1,0]
	s_nop 0
	v_div_scale_f32 v154, s[2:3], v151, v151, 1.0
	v_rcp_f32_e32 v155, v154
	s_nop 0
	v_fma_f32 v158, -v154, v155, 1.0
	v_fmac_f32_e32 v155, v158, v155
	v_div_scale_f32 v158, vcc, 1.0, v151, 1.0
	v_mul_f32_e32 v159, v158, v155
	v_fma_f32 v192, -v154, v159, v158
	v_fmac_f32_e32 v159, v192, v155
	v_fma_f32 v154, -v154, v159, v158
	v_div_fmas_f32 v154, v154, v155, v159
	v_div_fixup_f32 v151, v154, v151, 1.0
	v_div_scale_f32 v154, s[2:3], v150, v150, 1.0
	v_rcp_f32_e32 v155, v154
	s_nop 0
	v_fma_f32 v158, -v154, v155, 1.0
	v_fmac_f32_e32 v155, v158, v155
	v_div_scale_f32 v158, vcc, 1.0, v150, 1.0
	v_mul_f32_e32 v159, v158, v155
	v_fma_f32 v192, -v154, v159, v158
	v_fmac_f32_e32 v159, v192, v155
	v_fma_f32 v154, -v154, v159, v158
	v_div_fmas_f32 v154, v154, v155, v159
	v_div_fixup_f32 v150, v154, v150, 1.0
	v_pk_mul_f32 v[146:147], v[146:147], v[150:151]
	v_cndmask_b32_e64 v151, v223, v225, s[14:15]
	v_cndmask_b32_e64 v150, v219, v221, s[14:15]
	v_pk_fma_f32 v[150:151], v[156:157], v[150:151], v[160:161]
	v_cndmask_b32_e64 v155, v222, v224, s[16:17]
	v_cndmask_b32_e64 v154, v218, v220, s[16:17]
	v_pk_fma_f32 v[148:149], v[148:149], v[154:155], v[150:151]
	v_pk_mul_f32 v[146:147], v[4:5], v[146:147]
	v_pk_fma_f32 v[148:149], v[14:15], v[152:153], v[148:149]
	s_nop 0
	v_mul_f32_e32 v150, 0xbfb8aa3b, v148
	v_mul_f32_e32 v151, 0xbfb8aa3b, v149
	v_exp_f32_e32 v150, v150
	v_exp_f32_e32 v151, v151
	s_nop 0
	v_pk_add_f32 v[150:151], v[150:151], 1.0 op_sel_hi:[1,0]
	s_nop 0
	v_div_scale_f32 v152, s[2:3], v151, v151, 1.0
	v_rcp_f32_e32 v153, v152
	s_nop 0
	v_fma_f32 v154, -v152, v153, 1.0
	v_fmac_f32_e32 v153, v154, v153
	v_div_scale_f32 v154, vcc, 1.0, v151, 1.0
	v_mul_f32_e32 v155, v154, v153
	v_fma_f32 v156, -v152, v155, v154
	v_fmac_f32_e32 v155, v156, v153
	v_fma_f32 v152, -v152, v155, v154
	v_div_fmas_f32 v152, v152, v153, v155
	v_div_fixup_f32 v151, v152, v151, 1.0
	v_div_scale_f32 v152, s[2:3], v150, v150, 1.0
	v_rcp_f32_e32 v153, v152
	s_nop 0
	v_fma_f32 v154, -v152, v153, 1.0
	v_fmac_f32_e32 v153, v154, v153
	v_div_scale_f32 v154, vcc, 1.0, v150, 1.0
	v_mul_f32_e32 v155, v154, v153
	v_fma_f32 v156, -v152, v155, v154
	v_fmac_f32_e32 v155, v156, v153
	v_fma_f32 v152, -v152, v155, v154
	v_div_fmas_f32 v152, v152, v153, v155
	v_div_fixup_f32 v150, v152, v150, 1.0
	v_pk_mul_f32 v[148:149], v[148:149], v[150:151]
	v_cndmask_b32_e64 v151, v176, v177, s[14:15]
	v_cndmask_b32_e64 v150, v173, v175, s[14:15]
	s_waitcnt vmcnt(0)
	v_pk_fma_f32 v[130:131], v[130:131], v[150:151], v[142:143]
	v_cndmask_b32_e64 v143, v172, v174, s[16:17]
	v_cndmask_b32_e64 v142, v170, v171, s[16:17]
	v_pk_fma_f32 v[130:131], v[138:139], v[142:143], v[130:131]
	v_pk_mul_f32 v[148:149], v[6:7], v[148:149]
	v_pk_fma_f32 v[130:131], v[8:9], v[134:135], v[130:131]
	s_nop 0
	v_mul_f32_e32 v134, 0xbfb8aa3b, v130
	v_mul_f32_e32 v135, 0xbfb8aa3b, v131
	v_exp_f32_e32 v134, v134
	v_exp_f32_e32 v135, v135
	s_nop 0
	v_pk_add_f32 v[134:135], v[134:135], 1.0 op_sel_hi:[1,0]
	s_nop 0
	v_div_scale_f32 v138, s[2:3], v135, v135, 1.0
	v_rcp_f32_e32 v139, v138
	s_nop 0
	v_fma_f32 v142, -v138, v139, 1.0
	v_fmac_f32_e32 v139, v142, v139
	v_div_scale_f32 v142, vcc, 1.0, v135, 1.0
	v_mul_f32_e32 v143, v142, v139
	v_fma_f32 v150, -v138, v143, v142
	v_fmac_f32_e32 v143, v150, v139
	v_fma_f32 v138, -v138, v143, v142
	v_div_fmas_f32 v138, v138, v139, v143
	v_div_fixup_f32 v135, v138, v135, 1.0
	v_div_scale_f32 v138, s[2:3], v134, v134, 1.0
	v_rcp_f32_e32 v139, v138
	s_nop 0
	v_fma_f32 v142, -v138, v139, 1.0
	v_fmac_f32_e32 v139, v142, v139
	v_div_scale_f32 v142, vcc, 1.0, v134, 1.0
	v_mul_f32_e32 v143, v142, v139
	v_fma_f32 v150, -v138, v143, v142
	v_fmac_f32_e32 v143, v150, v139
	v_fma_f32 v138, -v138, v143, v142
	v_div_fmas_f32 v138, v138, v139, v143
	v_div_fixup_f32 v134, v138, v134, 1.0
	v_pk_mul_f32 v[130:131], v[130:131], v[134:135]
	v_cndmask_b32_e64 v139, v165, v167, s[16:17]
	v_pk_mul_f32 v[134:135], v[0:1], v[130:131]
	v_cndmask_b32_e64 v131, v168, v169, s[14:15]
	v_cndmask_b32_e64 v130, v164, v166, s[14:15]
	v_cndmask_b32_e64 v138, v162, v163, s[16:17]
	v_pk_fma_f32 v[130:131], v[132:133], v[130:131], v[144:145]
	s_nop 0
	v_pk_fma_f32 v[130:131], v[140:141], v[138:139], v[130:131]
	s_nop 0
	v_pk_fma_f32 v[130:131], v[10:11], v[136:137], v[130:131]
	s_nop 0
	v_mul_f32_e32 v132, 0xbfb8aa3b, v130
	v_mul_f32_e32 v133, 0xbfb8aa3b, v131
	v_exp_f32_e32 v132, v132
	v_exp_f32_e32 v133, v133
	s_nop 0
	v_pk_add_f32 v[132:133], v[132:133], 1.0 op_sel_hi:[1,0]
	s_nop 0
	v_div_scale_f32 v136, s[2:3], v133, v133, 1.0
	v_rcp_f32_e32 v137, v136
	s_nop 0
	v_fma_f32 v138, -v136, v137, 1.0
	v_fmac_f32_e32 v137, v138, v137
	v_div_scale_f32 v138, vcc, 1.0, v133, 1.0
	v_mul_f32_e32 v139, v138, v137
	v_fma_f32 v140, -v136, v139, v138
	v_fmac_f32_e32 v139, v140, v137
	v_fma_f32 v136, -v136, v139, v138
	v_div_fmas_f32 v136, v136, v137, v139
	v_div_fixup_f32 v133, v136, v133, 1.0
	v_div_scale_f32 v136, s[2:3], v132, v132, 1.0
	v_rcp_f32_e32 v137, v136
	s_nop 0
	v_fma_f32 v138, -v136, v137, 1.0
	v_fmac_f32_e32 v137, v138, v137
	v_div_scale_f32 v138, vcc, 1.0, v132, 1.0
	v_mul_f32_e32 v139, v138, v137
	v_fma_f32 v140, -v136, v139, v138
	v_fmac_f32_e32 v139, v140, v137
	v_fma_f32 v136, -v136, v139, v138
	v_div_fmas_f32 v136, v136, v137, v139
	v_div_fixup_f32 v132, v136, v132, 1.0
	v_pk_mul_f32 v[130:131], v[130:131], v[132:133]
	v_cvt_pk_bf16_f32 v132, v134, v135
	v_pk_mul_f32 v[136:137], v[2:3], v[130:131]
	v_cvt_pk_bf16_f32 v130, v146, v147
	v_cvt_pk_bf16_f32 v131, v148, v149
	v_cvt_pk_bf16_f32 v133, v136, v137
	v_mad_i64_i32 v[134:135], s[2:3], v16, s40, v[190:191]
	global_store_dwordx4 v[134:135], v[130:133], off
	s_barrier
